# v110 with the per-phase s_setprio toggles removed from the GEMM K-loops
# speedup vs baseline: 1.0158x; 1.0068x over previous
.LBB0_245:
	s_ashr_i32 s61, s60, 31
	s_xor_b64 s[76:77], s[40:41], -1
	s_lshl_b64 s[2:3], s[60:61], 19
	s_add_u32 s62, s86, s2
	s_addc_u32 s63, s87, s3
	s_and_b64 s[2:3], s[40:41], exec
	s_cselect_b32 s1, s63, s19
	s_cselect_b32 s2, s62, s18
	s_ashr_i32 s59, s58, 31
	s_lshl_b64 s[4:5], s[58:59], 19
	s_add_u32 s92, s28, s4
	s_addc_u32 s93, s29, s5
	s_and_b64 s[4:5], s[40:41], exec
	s_cselect_b32 s3, s93, s7
	s_cselect_b32 s4, s92, s6
	s_add_u32 s40, s18, 0x40080
	s_addc_u32 s41, s19, 0
	s_add_u32 s5, s6, 0x100
	s_addc_u32 s17, s7, 0
	s_mov_b32 s20, -2
	s_add_u32 s6, s40, 0xfffc0080
	s_addc_u32 s7, s41, -1
	s_add_i32 s21, s69, 0x100
	v_add_u32_e32 v0, s21, v151
	ds_read_b128 v[158:161], v0
	ds_read_b128 v[162:165], v0 offset:1024
	ds_read_b128 v[174:177], v0 offset:2048
	ds_read_b128 v[178:181], v0 offset:3072
	s_cmp_eq_u32 s20, 12
	s_cselect_b32 s19, s1, s7
	s_cselect_b32 s18, s2, s6
	s_cselect_b32 s7, s3, s17
	s_cselect_b32 s6, s4, s5
	v_lshl_add_u64 v[226:227], s[40:41], 0, v[154:155]
	s_add_i32 m0, s11, 0xc000
	ds_read_b128 v[182:185], v172
	ds_read_b128 v[186:189], v172 offset:1024
	ds_read_b128 v[190:193], v172 offset:2048
	ds_read_b128 v[206:209], v172 offset:3072
	ds_read_b128 v[210:213], v172 offset:4096
	ds_read_b128 v[214:217], v172 offset:5120
	ds_read_b128 v[218:221], v172 offset:6144
	ds_read_b128 v[222:225], v172 offset:7168
	global_load_lds_dwordx4 v[226:227], off
	v_lshl_add_u64 v[226:227], s[40:41], 0, v[156:157]
	s_add_i32 m0, s11, 0xe000
	s_nop 0
	global_load_lds_dwordx4 v[226:227], off
	s_waitcnt lgkmcnt(8)
	s_barrier
	s_waitcnt lgkmcnt(0)
	s_waitcnt lgkmcnt(0)
	v_mfma_f32_16x16x32_bf16 v[126:129], v[158:161], v[182:185], 0
	v_mfma_f32_16x16x32_bf16 v[122:125], v[174:177], v[182:185], 0
	v_mfma_f32_16x16x32_bf16 v[110:113], v[158:161], v[190:193], 0
	v_mfma_f32_16x16x32_bf16 v[106:109], v[174:177], v[190:193], 0
	v_mfma_f32_16x16x32_bf16 v[94:97], v[158:161], v[210:213], 0
	v_mfma_f32_16x16x32_bf16 v[90:93], v[174:177], v[210:213], 0
	v_mfma_f32_16x16x32_bf16 v[78:81], v[158:161], v[218:221], 0
	v_mfma_f32_16x16x32_bf16 v[74:77], v[174:177], v[218:221], 0
	v_mfma_f32_16x16x32_bf16 v[126:129], v[162:165], v[186:189], v[126:129]
	v_mfma_f32_16x16x32_bf16 v[122:125], v[178:181], v[186:189], v[122:125]
	v_mfma_f32_16x16x32_bf16 v[110:113], v[162:165], v[206:209], v[110:113]
	v_mfma_f32_16x16x32_bf16 v[106:109], v[178:181], v[206:209], v[106:109]
	v_mfma_f32_16x16x32_bf16 v[94:97], v[162:165], v[214:217], v[94:97]
	v_mfma_f32_16x16x32_bf16 v[90:93], v[178:181], v[214:217], v[90:93]
	v_mfma_f32_16x16x32_bf16 v[78:81], v[162:165], v[222:225], v[78:81]
	v_mfma_f32_16x16x32_bf16 v[74:77], v[178:181], v[222:225], v[74:77]
	s_barrier
	s_add_i32 s24, s96, 0x100
	s_add_i32 s21, s21, s10
	v_add_u32_e32 v0, s24, v151
	v_lshl_add_u64 v[242:243], s[6:7], 0, v[132:133]
	s_mov_b32 m0, s21
	ds_read_b128 v[226:229], v0
	ds_read_b128 v[230:233], v0 offset:1024
	ds_read_b128 v[234:237], v0 offset:2048
	ds_read_b128 v[238:241], v0 offset:3072
	global_load_lds_dwordx4 v[242:243], off
	v_lshl_add_u64 v[244:245], s[6:7], 0, v[136:137]
	s_add_i32 m0, s21, 0x2000
	s_nop 0
	global_load_lds_dwordx4 v[244:245], off
	s_barrier
	s_waitcnt lgkmcnt(0)
	s_waitcnt lgkmcnt(0)
	v_mfma_f32_16x16x32_bf16 v[118:121], v[226:229], v[182:185], 0
	v_mfma_f32_16x16x32_bf16 v[114:117], v[234:237], v[182:185], 0
	v_mfma_f32_16x16x32_bf16 v[102:105], v[226:229], v[190:193], 0
	v_mfma_f32_16x16x32_bf16 v[98:101], v[234:237], v[190:193], 0
	v_mfma_f32_16x16x32_bf16 v[86:89], v[226:229], v[210:213], 0
	v_mfma_f32_16x16x32_bf16 v[82:85], v[234:237], v[210:213], 0
	v_mfma_f32_16x16x32_bf16 v[70:73], v[226:229], v[218:221], 0
	v_mfma_f32_16x16x32_bf16 v[66:69], v[234:237], v[218:221], 0
	v_mfma_f32_16x16x32_bf16 v[118:121], v[230:233], v[186:189], v[118:121]
	v_mfma_f32_16x16x32_bf16 v[114:117], v[238:241], v[186:189], v[114:117]
	v_mfma_f32_16x16x32_bf16 v[102:105], v[230:233], v[206:209], v[102:105]
	v_mfma_f32_16x16x32_bf16 v[98:101], v[238:241], v[206:209], v[98:101]
	v_mfma_f32_16x16x32_bf16 v[86:89], v[230:233], v[214:217], v[86:89]
	v_mfma_f32_16x16x32_bf16 v[82:85], v[238:241], v[214:217], v[82:85]
	v_mfma_f32_16x16x32_bf16 v[70:73], v[230:233], v[222:225], v[70:73]
	v_mfma_f32_16x16x32_bf16 v[66:69], v[238:241], v[222:225], v[66:69]
	s_mov_b32 m0, s11
	v_lshl_add_u64 v[246:247], s[18:19], 0, v[130:131]
	s_barrier
	ds_read_b128 v[182:185], v172 offset:16384
	ds_read_b128 v[186:189], v172 offset:17408
	ds_read_b128 v[190:193], v172 offset:18432
	ds_read_b128 v[206:209], v172 offset:19456
	ds_read_b128 v[210:213], v172 offset:20480
	ds_read_b128 v[214:217], v172 offset:21504
	ds_read_b128 v[218:221], v172 offset:22528
	ds_read_b128 v[222:225], v172 offset:23552
	global_load_lds_dwordx4 v[246:247], off
	v_lshl_add_u64 v[248:249], s[18:19], 0, v[134:135]
	s_mov_b32 m0, s12
	s_nop 0
	global_load_lds_dwordx4 v[248:249], off
	s_barrier
	s_waitcnt lgkmcnt(0)
	s_waitcnt lgkmcnt(0)
	v_mfma_f32_16x16x32_bf16 v[62:65], v[158:161], v[182:185], 0
	v_mfma_f32_16x16x32_bf16 v[58:61], v[174:177], v[182:185], 0
	v_mfma_f32_16x16x32_bf16 v[46:49], v[158:161], v[190:193], 0
	v_mfma_f32_16x16x32_bf16 v[42:45], v[174:177], v[190:193], 0
	v_mfma_f32_16x16x32_bf16 v[30:33], v[158:161], v[210:213], 0
	v_mfma_f32_16x16x32_bf16 v[26:29], v[174:177], v[210:213], 0
	v_mfma_f32_16x16x32_bf16 v[14:17], v[158:161], v[218:221], 0
	v_mfma_f32_16x16x32_bf16 v[10:13], v[174:177], v[218:221], 0
	v_mfma_f32_16x16x32_bf16 v[62:65], v[162:165], v[186:189], v[62:65]
	v_mfma_f32_16x16x32_bf16 v[58:61], v[178:181], v[186:189], v[58:61]
	v_mfma_f32_16x16x32_bf16 v[46:49], v[162:165], v[206:209], v[46:49]
	v_mfma_f32_16x16x32_bf16 v[42:45], v[178:181], v[206:209], v[42:45]
	v_mfma_f32_16x16x32_bf16 v[30:33], v[162:165], v[214:217], v[30:33]
	v_mfma_f32_16x16x32_bf16 v[26:29], v[178:181], v[214:217], v[26:29]
	v_mfma_f32_16x16x32_bf16 v[14:17], v[162:165], v[222:225], v[14:17]
	v_mfma_f32_16x16x32_bf16 v[10:13], v[178:181], v[222:225], v[10:13]
	s_barrier
	s_add_u32 s22, s6, 0x40000
	s_addc_u32 s23, s7, 0
	s_add_i32 s21, s24, s10
	v_lshl_add_u64 v[158:159], s[22:23], 0, v[132:133]
	s_mov_b32 m0, s21
	s_nop 0
	global_load_lds_dwordx4 v[158:159], off
	v_lshl_add_u64 v[158:159], s[22:23], 0, v[136:137]
	s_add_i32 m0, s21, 0x2000
	s_nop 0
	global_load_lds_dwordx4 v[158:159], off
	s_waitcnt vmcnt(6)
	s_barrier
	v_mfma_f32_16x16x32_bf16 v[54:57], v[226:229], v[182:185], 0
	v_mfma_f32_16x16x32_bf16 v[50:53], v[234:237], v[182:185], 0
	v_mfma_f32_16x16x32_bf16 v[38:41], v[226:229], v[190:193], 0
	v_mfma_f32_16x16x32_bf16 v[34:37], v[234:237], v[190:193], 0
	v_mfma_f32_16x16x32_bf16 v[22:25], v[226:229], v[210:213], 0
	v_mfma_f32_16x16x32_bf16 v[18:21], v[234:237], v[210:213], 0
	v_mfma_f32_16x16x32_bf16 v[6:9], v[226:229], v[218:221], 0
	v_mfma_f32_16x16x32_bf16 v[2:5], v[234:237], v[218:221], 0
	v_mfma_f32_16x16x32_bf16 v[54:57], v[230:233], v[186:189], v[54:57]
	v_mfma_f32_16x16x32_bf16 v[50:53], v[238:241], v[186:189], v[50:53]
	v_mfma_f32_16x16x32_bf16 v[38:41], v[230:233], v[206:209], v[38:41]
	v_mfma_f32_16x16x32_bf16 v[34:37], v[238:241], v[206:209], v[34:37]
	v_mfma_f32_16x16x32_bf16 v[22:25], v[230:233], v[214:217], v[22:25]
	v_mfma_f32_16x16x32_bf16 v[18:21], v[238:241], v[214:217], v[18:21]
	v_mfma_f32_16x16x32_bf16 v[6:9], v[230:233], v[222:225], v[6:9]
	v_mfma_f32_16x16x32_bf16 v[2:5], v[238:241], v[222:225], v[2:5]
	s_add_i32 s21, s97, 0x100
	v_add_u32_e32 v0, s21, v151
	s_barrier
	ds_read_b128 v[158:161], v0
	ds_read_b128 v[162:165], v0 offset:1024
	ds_read_b128 v[174:177], v0 offset:2048
	ds_read_b128 v[178:181], v0 offset:3072
	s_add_u32 s18, s18, 0x40000
	s_addc_u32 s19, s19, 0
	s_mov_b32 m0, s13
	v_lshl_add_u64 v[226:227], s[18:19], 0, v[130:131]
	ds_read_b128 v[182:185], v172 offset:32768
	ds_read_b128 v[186:189], v172 offset:33792
	ds_read_b128 v[190:193], v172 offset:34816
	ds_read_b128 v[206:209], v172 offset:35840
	ds_read_b128 v[210:213], v172 offset:36864
	ds_read_b128 v[214:217], v172 offset:37888
	ds_read_b128 v[218:221], v172 offset:38912
	ds_read_b128 v[222:225], v172 offset:39936
	global_load_lds_dwordx4 v[226:227], off
	v_lshl_add_u64 v[226:227], s[18:19], 0, v[134:135]
	s_mov_b32 m0, s45
	s_nop 0
	global_load_lds_dwordx4 v[226:227], off
	s_waitcnt lgkmcnt(8)
	s_barrier
	s_waitcnt lgkmcnt(0)
	s_waitcnt lgkmcnt(0)
	v_mfma_f32_16x16x32_bf16 v[126:129], v[158:161], v[182:185], v[126:129]
	v_mfma_f32_16x16x32_bf16 v[122:125], v[174:177], v[182:185], v[122:125]
	v_mfma_f32_16x16x32_bf16 v[110:113], v[158:161], v[190:193], v[110:113]
	v_mfma_f32_16x16x32_bf16 v[106:109], v[174:177], v[190:193], v[106:109]
	v_mfma_f32_16x16x32_bf16 v[94:97], v[158:161], v[210:213], v[94:97]
	v_mfma_f32_16x16x32_bf16 v[90:93], v[174:177], v[210:213], v[90:93]
	v_mfma_f32_16x16x32_bf16 v[78:81], v[158:161], v[218:221], v[78:81]
	v_mfma_f32_16x16x32_bf16 v[74:77], v[174:177], v[218:221], v[74:77]
	v_mfma_f32_16x16x32_bf16 v[126:129], v[162:165], v[186:189], v[126:129]
	v_mfma_f32_16x16x32_bf16 v[122:125], v[178:181], v[186:189], v[122:125]
	v_mfma_f32_16x16x32_bf16 v[110:113], v[162:165], v[206:209], v[110:113]
	v_mfma_f32_16x16x32_bf16 v[106:109], v[178:181], v[206:209], v[106:109]
	v_mfma_f32_16x16x32_bf16 v[94:97], v[162:165], v[214:217], v[94:97]
	v_mfma_f32_16x16x32_bf16 v[90:93], v[178:181], v[214:217], v[90:93]
	v_mfma_f32_16x16x32_bf16 v[78:81], v[162:165], v[222:225], v[78:81]
	v_mfma_f32_16x16x32_bf16 v[74:77], v[178:181], v[222:225], v[74:77]
	s_barrier
	s_add_i32 s18, s44, 0x100
	s_add_i32 s19, s21, s10
	v_add_u32_e32 v0, s18, v151
	v_lshl_add_u64 v[242:243], v[242:243], 0, s[46:47]
	s_mov_b32 m0, s19
	ds_read_b128 v[226:229], v0
	ds_read_b128 v[230:233], v0 offset:1024
	ds_read_b128 v[234:237], v0 offset:2048
	ds_read_b128 v[238:241], v0 offset:3072
	global_load_lds_dwordx4 v[242:243], off
	v_lshl_add_u64 v[242:243], v[244:245], 0, s[46:47]
	s_add_i32 m0, s19, 0x2000
	s_nop 0
	global_load_lds_dwordx4 v[242:243], off
	s_barrier
	s_waitcnt lgkmcnt(0)
	s_waitcnt lgkmcnt(0)
	v_mfma_f32_16x16x32_bf16 v[118:121], v[226:229], v[182:185], v[118:121]
	v_mfma_f32_16x16x32_bf16 v[114:117], v[234:237], v[182:185], v[114:117]
	v_mfma_f32_16x16x32_bf16 v[102:105], v[226:229], v[190:193], v[102:105]
	v_mfma_f32_16x16x32_bf16 v[98:101], v[234:237], v[190:193], v[98:101]
	v_mfma_f32_16x16x32_bf16 v[86:89], v[226:229], v[210:213], v[86:89]
	v_mfma_f32_16x16x32_bf16 v[82:85], v[234:237], v[210:213], v[82:85]
	v_mfma_f32_16x16x32_bf16 v[70:73], v[226:229], v[218:221], v[70:73]
	v_mfma_f32_16x16x32_bf16 v[66:69], v[234:237], v[218:221], v[66:69]
	v_mfma_f32_16x16x32_bf16 v[118:121], v[230:233], v[186:189], v[118:121]
	v_mfma_f32_16x16x32_bf16 v[114:117], v[238:241], v[186:189], v[114:117]
	v_mfma_f32_16x16x32_bf16 v[102:105], v[230:233], v[206:209], v[102:105]
	v_mfma_f32_16x16x32_bf16 v[98:101], v[238:241], v[206:209], v[98:101]
	v_mfma_f32_16x16x32_bf16 v[86:89], v[230:233], v[214:217], v[86:89]
	v_mfma_f32_16x16x32_bf16 v[82:85], v[238:241], v[214:217], v[82:85]
	v_mfma_f32_16x16x32_bf16 v[70:73], v[230:233], v[222:225], v[70:73]
	v_mfma_f32_16x16x32_bf16 v[66:69], v[238:241], v[222:225], v[66:69]
	s_mov_b32 m0, s14
	v_lshl_add_u64 v[242:243], v[246:247], 0, s[46:47]
	s_barrier
	ds_read_b128 v[182:185], v172 offset:49152
	ds_read_b128 v[186:189], v172 offset:50176
	ds_read_b128 v[190:193], v172 offset:51200
	ds_read_b128 v[206:209], v172 offset:52224
	ds_read_b128 v[210:213], v172 offset:53248
	ds_read_b128 v[214:217], v172 offset:54272
	ds_read_b128 v[218:221], v172 offset:55296
	ds_read_b128 v[222:225], v172 offset:56320
	global_load_lds_dwordx4 v[242:243], off
	v_lshl_add_u64 v[242:243], v[248:249], 0, s[46:47]
	s_mov_b32 m0, s15
	s_nop 0
	global_load_lds_dwordx4 v[242:243], off
	s_barrier
	s_waitcnt lgkmcnt(0)
	s_waitcnt lgkmcnt(0)
	v_mfma_f32_16x16x32_bf16 v[62:65], v[158:161], v[182:185], v[62:65]
	v_mfma_f32_16x16x32_bf16 v[58:61], v[174:177], v[182:185], v[58:61]
	v_mfma_f32_16x16x32_bf16 v[46:49], v[158:161], v[190:193], v[46:49]
	v_mfma_f32_16x16x32_bf16 v[42:45], v[174:177], v[190:193], v[42:45]
	v_mfma_f32_16x16x32_bf16 v[30:33], v[158:161], v[210:213], v[30:33]
	v_mfma_f32_16x16x32_bf16 v[26:29], v[174:177], v[210:213], v[26:29]
	v_mfma_f32_16x16x32_bf16 v[14:17], v[158:161], v[218:221], v[14:17]
	v_mfma_f32_16x16x32_bf16 v[10:13], v[174:177], v[218:221], v[10:13]
	v_mfma_f32_16x16x32_bf16 v[62:65], v[162:165], v[186:189], v[62:65]
	v_mfma_f32_16x16x32_bf16 v[58:61], v[178:181], v[186:189], v[58:61]
	v_mfma_f32_16x16x32_bf16 v[46:49], v[162:165], v[206:209], v[46:49]
	v_mfma_f32_16x16x32_bf16 v[42:45], v[178:181], v[206:209], v[42:45]
	v_mfma_f32_16x16x32_bf16 v[30:33], v[162:165], v[214:217], v[30:33]
	v_mfma_f32_16x16x32_bf16 v[26:29], v[178:181], v[214:217], v[26:29]
	v_mfma_f32_16x16x32_bf16 v[14:17], v[162:165], v[222:225], v[14:17]
	v_mfma_f32_16x16x32_bf16 v[10:13], v[178:181], v[222:225], v[10:13]
	s_barrier
	s_add_u32 s6, s6, 0x40080
	s_addc_u32 s7, s7, 0
	s_add_i32 s18, s18, s10
	v_lshl_add_u64 v[158:159], s[6:7], 0, v[132:133]
	s_mov_b32 m0, s18
	s_nop 0
	global_load_lds_dwordx4 v[158:159], off
	v_lshl_add_u64 v[158:159], s[6:7], 0, v[136:137]
	s_add_i32 m0, s18, 0x2000
	s_nop 0
	global_load_lds_dwordx4 v[158:159], off
	s_waitcnt vmcnt(6)
	s_barrier
	v_mfma_f32_16x16x32_bf16 v[54:57], v[226:229], v[182:185], v[54:57]
	v_mfma_f32_16x16x32_bf16 v[50:53], v[234:237], v[182:185], v[50:53]
	v_mfma_f32_16x16x32_bf16 v[38:41], v[226:229], v[190:193], v[38:41]
	v_mfma_f32_16x16x32_bf16 v[34:37], v[234:237], v[190:193], v[34:37]
	v_mfma_f32_16x16x32_bf16 v[22:25], v[226:229], v[210:213], v[22:25]
	v_mfma_f32_16x16x32_bf16 v[18:21], v[234:237], v[210:213], v[18:21]
	v_mfma_f32_16x16x32_bf16 v[6:9], v[226:229], v[218:221], v[6:9]
	v_mfma_f32_16x16x32_bf16 v[2:5], v[234:237], v[218:221], v[2:5]
	v_mfma_f32_16x16x32_bf16 v[54:57], v[230:233], v[186:189], v[54:57]
	v_mfma_f32_16x16x32_bf16 v[50:53], v[238:241], v[186:189], v[50:53]
	v_mfma_f32_16x16x32_bf16 v[38:41], v[230:233], v[206:209], v[38:41]
	v_mfma_f32_16x16x32_bf16 v[34:37], v[238:241], v[206:209], v[34:37]
	v_mfma_f32_16x16x32_bf16 v[22:25], v[230:233], v[214:217], v[22:25]
	v_mfma_f32_16x16x32_bf16 v[18:21], v[238:241], v[214:217], v[18:21]
	v_mfma_f32_16x16x32_bf16 v[6:9], v[230:233], v[222:225], v[6:9]
	v_mfma_f32_16x16x32_bf16 v[2:5], v[238:241], v[222:225], v[2:5]
	s_add_i32 s20, s20, 2
	s_add_u32 s40, s40, 0x100
	s_addc_u32 s41, s41, 0
	s_add_u32 s5, s5, 0x100
	s_addc_u32 s17, s17, 0
	s_cmp_gt_u32 s20, 13
	s_barrier
	s_cbranch_scc1 .Lmy_kexit0
.LBB0_246:
	s_add_u32 s6, s40, 0xfffc0080
	s_addc_u32 s7, s41, -1
	s_add_i32 s21, s69, 0x100
	v_add_u32_e32 v0, s21, v151
	ds_read_b128 v[158:161], v0
	ds_read_b128 v[162:165], v0 offset:1024
	ds_read_b128 v[174:177], v0 offset:2048
	ds_read_b128 v[178:181], v0 offset:3072
	s_cmp_eq_u32 s20, 12
	s_cselect_b32 s19, s1, s7
	s_cselect_b32 s18, s2, s6
	s_cselect_b32 s7, s3, s17
	s_cselect_b32 s6, s4, s5
	v_lshl_add_u64 v[226:227], s[40:41], 0, v[154:155]
	s_add_i32 m0, s11, 0xc000
	ds_read_b128 v[182:185], v172
	ds_read_b128 v[186:189], v172 offset:1024
	ds_read_b128 v[190:193], v172 offset:2048
	ds_read_b128 v[206:209], v172 offset:3072
	ds_read_b128 v[210:213], v172 offset:4096
	ds_read_b128 v[214:217], v172 offset:5120
	ds_read_b128 v[218:221], v172 offset:6144
	ds_read_b128 v[222:225], v172 offset:7168
	global_load_lds_dwordx4 v[226:227], off
	v_lshl_add_u64 v[226:227], s[40:41], 0, v[156:157]
	s_add_i32 m0, s11, 0xe000
	s_nop 0
	global_load_lds_dwordx4 v[226:227], off
	s_waitcnt lgkmcnt(8)
	s_barrier
	s_waitcnt lgkmcnt(0)
	s_waitcnt lgkmcnt(0)
	v_mfma_f32_16x16x32_bf16 v[126:129], v[158:161], v[182:185], v[126:129]
	v_mfma_f32_16x16x32_bf16 v[122:125], v[174:177], v[182:185], v[122:125]
	v_mfma_f32_16x16x32_bf16 v[110:113], v[158:161], v[190:193], v[110:113]
	v_mfma_f32_16x16x32_bf16 v[106:109], v[174:177], v[190:193], v[106:109]
	v_mfma_f32_16x16x32_bf16 v[94:97], v[158:161], v[210:213], v[94:97]
	v_mfma_f32_16x16x32_bf16 v[90:93], v[174:177], v[210:213], v[90:93]
	v_mfma_f32_16x16x32_bf16 v[78:81], v[158:161], v[218:221], v[78:81]
	v_mfma_f32_16x16x32_bf16 v[74:77], v[174:177], v[218:221], v[74:77]
	v_mfma_f32_16x16x32_bf16 v[126:129], v[162:165], v[186:189], v[126:129]
	v_mfma_f32_16x16x32_bf16 v[122:125], v[178:181], v[186:189], v[122:125]
	v_mfma_f32_16x16x32_bf16 v[110:113], v[162:165], v[206:209], v[110:113]
	v_mfma_f32_16x16x32_bf16 v[106:109], v[178:181], v[206:209], v[106:109]
	v_mfma_f32_16x16x32_bf16 v[94:97], v[162:165], v[214:217], v[94:97]
	v_mfma_f32_16x16x32_bf16 v[90:93], v[178:181], v[214:217], v[90:93]
	v_mfma_f32_16x16x32_bf16 v[78:81], v[162:165], v[222:225], v[78:81]
	v_mfma_f32_16x16x32_bf16 v[74:77], v[178:181], v[222:225], v[74:77]
	s_barrier
	s_add_i32 s24, s96, 0x100
	s_add_i32 s21, s21, s10
	v_add_u32_e32 v0, s24, v151
	v_lshl_add_u64 v[242:243], s[6:7], 0, v[132:133]
	s_mov_b32 m0, s21
	ds_read_b128 v[226:229], v0
	ds_read_b128 v[230:233], v0 offset:1024
	ds_read_b128 v[234:237], v0 offset:2048
	ds_read_b128 v[238:241], v0 offset:3072
	global_load_lds_dwordx4 v[242:243], off
	v_lshl_add_u64 v[244:245], s[6:7], 0, v[136:137]
	s_add_i32 m0, s21, 0x2000
	s_nop 0
	global_load_lds_dwordx4 v[244:245], off
	s_barrier
	s_waitcnt lgkmcnt(0)
	s_waitcnt lgkmcnt(0)
	v_mfma_f32_16x16x32_bf16 v[118:121], v[226:229], v[182:185], v[118:121]
	v_mfma_f32_16x16x32_bf16 v[114:117], v[234:237], v[182:185], v[114:117]
	v_mfma_f32_16x16x32_bf16 v[102:105], v[226:229], v[190:193], v[102:105]
	v_mfma_f32_16x16x32_bf16 v[98:101], v[234:237], v[190:193], v[98:101]
	v_mfma_f32_16x16x32_bf16 v[86:89], v[226:229], v[210:213], v[86:89]
	v_mfma_f32_16x16x32_bf16 v[82:85], v[234:237], v[210:213], v[82:85]
	v_mfma_f32_16x16x32_bf16 v[70:73], v[226:229], v[218:221], v[70:73]
	v_mfma_f32_16x16x32_bf16 v[66:69], v[234:237], v[218:221], v[66:69]
	v_mfma_f32_16x16x32_bf16 v[118:121], v[230:233], v[186:189], v[118:121]
	v_mfma_f32_16x16x32_bf16 v[114:117], v[238:241], v[186:189], v[114:117]
	v_mfma_f32_16x16x32_bf16 v[102:105], v[230:233], v[206:209], v[102:105]
	v_mfma_f32_16x16x32_bf16 v[98:101], v[238:241], v[206:209], v[98:101]
	v_mfma_f32_16x16x32_bf16 v[86:89], v[230:233], v[214:217], v[86:89]
	v_mfma_f32_16x16x32_bf16 v[82:85], v[238:241], v[214:217], v[82:85]
	v_mfma_f32_16x16x32_bf16 v[70:73], v[230:233], v[222:225], v[70:73]
	v_mfma_f32_16x16x32_bf16 v[66:69], v[238:241], v[222:225], v[66:69]
	s_mov_b32 m0, s11
	v_lshl_add_u64 v[246:247], s[18:19], 0, v[130:131]
	s_barrier
	ds_read_b128 v[182:185], v172 offset:16384
	ds_read_b128 v[186:189], v172 offset:17408
	ds_read_b128 v[190:193], v172 offset:18432
	ds_read_b128 v[206:209], v172 offset:19456
	ds_read_b128 v[210:213], v172 offset:20480
	ds_read_b128 v[214:217], v172 offset:21504
	ds_read_b128 v[218:221], v172 offset:22528
	ds_read_b128 v[222:225], v172 offset:23552
	global_load_lds_dwordx4 v[246:247], off
	v_lshl_add_u64 v[248:249], s[18:19], 0, v[134:135]
	s_mov_b32 m0, s12
	s_nop 0
	global_load_lds_dwordx4 v[248:249], off
	s_barrier
	s_waitcnt lgkmcnt(0)
	s_waitcnt lgkmcnt(0)
	v_mfma_f32_16x16x32_bf16 v[62:65], v[158:161], v[182:185], v[62:65]
	v_mfma_f32_16x16x32_bf16 v[58:61], v[174:177], v[182:185], v[58:61]
	v_mfma_f32_16x16x32_bf16 v[46:49], v[158:161], v[190:193], v[46:49]
	v_mfma_f32_16x16x32_bf16 v[42:45], v[174:177], v[190:193], v[42:45]
	v_mfma_f32_16x16x32_bf16 v[30:33], v[158:161], v[210:213], v[30:33]
	v_mfma_f32_16x16x32_bf16 v[26:29], v[174:177], v[210:213], v[26:29]
	v_mfma_f32_16x16x32_bf16 v[14:17], v[158:161], v[218:221], v[14:17]
	v_mfma_f32_16x16x32_bf16 v[10:13], v[174:177], v[218:221], v[10:13]
	v_mfma_f32_16x16x32_bf16 v[62:65], v[162:165], v[186:189], v[62:65]
	v_mfma_f32_16x16x32_bf16 v[58:61], v[178:181], v[186:189], v[58:61]
	v_mfma_f32_16x16x32_bf16 v[46:49], v[162:165], v[206:209], v[46:49]
	v_mfma_f32_16x16x32_bf16 v[42:45], v[178:181], v[206:209], v[42:45]
	v_mfma_f32_16x16x32_bf16 v[30:33], v[162:165], v[214:217], v[30:33]
	v_mfma_f32_16x16x32_bf16 v[26:29], v[178:181], v[214:217], v[26:29]
	v_mfma_f32_16x16x32_bf16 v[14:17], v[162:165], v[222:225], v[14:17]
	v_mfma_f32_16x16x32_bf16 v[10:13], v[178:181], v[222:225], v[10:13]
	s_barrier
	s_add_u32 s22, s6, 0x40000
	s_addc_u32 s23, s7, 0
	s_add_i32 s21, s24, s10
	v_lshl_add_u64 v[158:159], s[22:23], 0, v[132:133]
	s_mov_b32 m0, s21
	s_nop 0
	global_load_lds_dwordx4 v[158:159], off
	v_lshl_add_u64 v[158:159], s[22:23], 0, v[136:137]
	s_add_i32 m0, s21, 0x2000
	s_nop 0
	global_load_lds_dwordx4 v[158:159], off
	s_waitcnt vmcnt(6)
	s_barrier
	v_mfma_f32_16x16x32_bf16 v[54:57], v[226:229], v[182:185], v[54:57]
	v_mfma_f32_16x16x32_bf16 v[50:53], v[234:237], v[182:185], v[50:53]
	v_mfma_f32_16x16x32_bf16 v[38:41], v[226:229], v[190:193], v[38:41]
	v_mfma_f32_16x16x32_bf16 v[34:37], v[234:237], v[190:193], v[34:37]
	v_mfma_f32_16x16x32_bf16 v[22:25], v[226:229], v[210:213], v[22:25]
	v_mfma_f32_16x16x32_bf16 v[18:21], v[234:237], v[210:213], v[18:21]
	v_mfma_f32_16x16x32_bf16 v[6:9], v[226:229], v[218:221], v[6:9]
	v_mfma_f32_16x16x32_bf16 v[2:5], v[234:237], v[218:221], v[2:5]
	v_mfma_f32_16x16x32_bf16 v[54:57], v[230:233], v[186:189], v[54:57]
	v_mfma_f32_16x16x32_bf16 v[50:53], v[238:241], v[186:189], v[50:53]
	v_mfma_f32_16x16x32_bf16 v[38:41], v[230:233], v[206:209], v[38:41]
	v_mfma_f32_16x16x32_bf16 v[34:37], v[238:241], v[206:209], v[34:37]
	v_mfma_f32_16x16x32_bf16 v[22:25], v[230:233], v[214:217], v[22:25]
	v_mfma_f32_16x16x32_bf16 v[18:21], v[238:241], v[214:217], v[18:21]
	v_mfma_f32_16x16x32_bf16 v[6:9], v[230:233], v[222:225], v[6:9]
	v_mfma_f32_16x16x32_bf16 v[2:5], v[238:241], v[222:225], v[2:5]
	s_add_i32 s21, s97, 0x100
	v_add_u32_e32 v0, s21, v151
	s_barrier
	ds_read_b128 v[158:161], v0
	ds_read_b128 v[162:165], v0 offset:1024
	ds_read_b128 v[174:177], v0 offset:2048
	ds_read_b128 v[178:181], v0 offset:3072
	s_add_u32 s18, s18, 0x40000
	s_addc_u32 s19, s19, 0
	s_mov_b32 m0, s13
	v_lshl_add_u64 v[226:227], s[18:19], 0, v[130:131]
	ds_read_b128 v[182:185], v172 offset:32768
	ds_read_b128 v[186:189], v172 offset:33792
	ds_read_b128 v[190:193], v172 offset:34816
	ds_read_b128 v[206:209], v172 offset:35840
	ds_read_b128 v[210:213], v172 offset:36864
	ds_read_b128 v[214:217], v172 offset:37888
	ds_read_b128 v[218:221], v172 offset:38912
	ds_read_b128 v[222:225], v172 offset:39936
	global_load_lds_dwordx4 v[226:227], off
	v_lshl_add_u64 v[226:227], s[18:19], 0, v[134:135]
	s_mov_b32 m0, s45
	s_nop 0
	global_load_lds_dwordx4 v[226:227], off
	s_waitcnt lgkmcnt(8)
	s_barrier
	s_waitcnt lgkmcnt(0)
	s_waitcnt lgkmcnt(0)
	v_mfma_f32_16x16x32_bf16 v[126:129], v[158:161], v[182:185], v[126:129]
	v_mfma_f32_16x16x32_bf16 v[122:125], v[174:177], v[182:185], v[122:125]
	v_mfma_f32_16x16x32_bf16 v[110:113], v[158:161], v[190:193], v[110:113]
	v_mfma_f32_16x16x32_bf16 v[106:109], v[174:177], v[190:193], v[106:109]
	v_mfma_f32_16x16x32_bf16 v[94:97], v[158:161], v[210:213], v[94:97]
	v_mfma_f32_16x16x32_bf16 v[90:93], v[174:177], v[210:213], v[90:93]
	v_mfma_f32_16x16x32_bf16 v[78:81], v[158:161], v[218:221], v[78:81]
	v_mfma_f32_16x16x32_bf16 v[74:77], v[174:177], v[218:221], v[74:77]
	v_mfma_f32_16x16x32_bf16 v[126:129], v[162:165], v[186:189], v[126:129]
	v_mfma_f32_16x16x32_bf16 v[122:125], v[178:181], v[186:189], v[122:125]
	v_mfma_f32_16x16x32_bf16 v[110:113], v[162:165], v[206:209], v[110:113]
	v_mfma_f32_16x16x32_bf16 v[106:109], v[178:181], v[206:209], v[106:109]
	v_mfma_f32_16x16x32_bf16 v[94:97], v[162:165], v[214:217], v[94:97]
	v_mfma_f32_16x16x32_bf16 v[90:93], v[178:181], v[214:217], v[90:93]
	v_mfma_f32_16x16x32_bf16 v[78:81], v[162:165], v[222:225], v[78:81]
	v_mfma_f32_16x16x32_bf16 v[74:77], v[178:181], v[222:225], v[74:77]
	s_barrier
	s_add_i32 s18, s44, 0x100
	s_add_i32 s19, s21, s10
	v_add_u32_e32 v0, s18, v151
	v_lshl_add_u64 v[242:243], v[242:243], 0, s[46:47]
	s_mov_b32 m0, s19
	ds_read_b128 v[226:229], v0
	ds_read_b128 v[230:233], v0 offset:1024
	ds_read_b128 v[234:237], v0 offset:2048
	ds_read_b128 v[238:241], v0 offset:3072
	global_load_lds_dwordx4 v[242:243], off
	v_lshl_add_u64 v[242:243], v[244:245], 0, s[46:47]
	s_add_i32 m0, s19, 0x2000
	s_nop 0
	global_load_lds_dwordx4 v[242:243], off
	s_barrier
	s_waitcnt lgkmcnt(0)
	s_waitcnt lgkmcnt(0)
	v_mfma_f32_16x16x32_bf16 v[118:121], v[226:229], v[182:185], v[118:121]
	v_mfma_f32_16x16x32_bf16 v[114:117], v[234:237], v[182:185], v[114:117]
	v_mfma_f32_16x16x32_bf16 v[102:105], v[226:229], v[190:193], v[102:105]
	v_mfma_f32_16x16x32_bf16 v[98:101], v[234:237], v[190:193], v[98:101]
	v_mfma_f32_16x16x32_bf16 v[86:89], v[226:229], v[210:213], v[86:89]
	v_mfma_f32_16x16x32_bf16 v[82:85], v[234:237], v[210:213], v[82:85]
	v_mfma_f32_16x16x32_bf16 v[70:73], v[226:229], v[218:221], v[70:73]
	v_mfma_f32_16x16x32_bf16 v[66:69], v[234:237], v[218:221], v[66:69]
	v_mfma_f32_16x16x32_bf16 v[118:121], v[230:233], v[186:189], v[118:121]
	v_mfma_f32_16x16x32_bf16 v[114:117], v[238:241], v[186:189], v[114:117]
	v_mfma_f32_16x16x32_bf16 v[102:105], v[230:233], v[206:209], v[102:105]
	v_mfma_f32_16x16x32_bf16 v[98:101], v[238:241], v[206:209], v[98:101]
	v_mfma_f32_16x16x32_bf16 v[86:89], v[230:233], v[214:217], v[86:89]
	v_mfma_f32_16x16x32_bf16 v[82:85], v[238:241], v[214:217], v[82:85]
	v_mfma_f32_16x16x32_bf16 v[70:73], v[230:233], v[222:225], v[70:73]
	v_mfma_f32_16x16x32_bf16 v[66:69], v[238:241], v[222:225], v[66:69]
	s_mov_b32 m0, s14
	v_lshl_add_u64 v[242:243], v[246:247], 0, s[46:47]
	s_barrier
	ds_read_b128 v[182:185], v172 offset:49152
	ds_read_b128 v[186:189], v172 offset:50176
	ds_read_b128 v[190:193], v172 offset:51200
	ds_read_b128 v[206:209], v172 offset:52224
	ds_read_b128 v[210:213], v172 offset:53248
	ds_read_b128 v[214:217], v172 offset:54272
	ds_read_b128 v[218:221], v172 offset:55296
	ds_read_b128 v[222:225], v172 offset:56320
	global_load_lds_dwordx4 v[242:243], off
	v_lshl_add_u64 v[242:243], v[248:249], 0, s[46:47]
	s_mov_b32 m0, s15
	s_nop 0
	global_load_lds_dwordx4 v[242:243], off
	s_barrier
	s_waitcnt lgkmcnt(0)
	s_waitcnt lgkmcnt(0)
	v_mfma_f32_16x16x32_bf16 v[62:65], v[158:161], v[182:185], v[62:65]
	v_mfma_f32_16x16x32_bf16 v[58:61], v[174:177], v[182:185], v[58:61]
	v_mfma_f32_16x16x32_bf16 v[46:49], v[158:161], v[190:193], v[46:49]
	v_mfma_f32_16x16x32_bf16 v[42:45], v[174:177], v[190:193], v[42:45]
	v_mfma_f32_16x16x32_bf16 v[30:33], v[158:161], v[210:213], v[30:33]
	v_mfma_f32_16x16x32_bf16 v[26:29], v[174:177], v[210:213], v[26:29]
	v_mfma_f32_16x16x32_bf16 v[14:17], v[158:161], v[218:221], v[14:17]
	v_mfma_f32_16x16x32_bf16 v[10:13], v[174:177], v[218:221], v[10:13]
	v_mfma_f32_16x16x32_bf16 v[62:65], v[162:165], v[186:189], v[62:65]
	v_mfma_f32_16x16x32_bf16 v[58:61], v[178:181], v[186:189], v[58:61]
	v_mfma_f32_16x16x32_bf16 v[46:49], v[162:165], v[206:209], v[46:49]
	v_mfma_f32_16x16x32_bf16 v[42:45], v[178:181], v[206:209], v[42:45]
	v_mfma_f32_16x16x32_bf16 v[30:33], v[162:165], v[214:217], v[30:33]
	v_mfma_f32_16x16x32_bf16 v[26:29], v[178:181], v[214:217], v[26:29]
	v_mfma_f32_16x16x32_bf16 v[14:17], v[162:165], v[222:225], v[14:17]
	v_mfma_f32_16x16x32_bf16 v[10:13], v[178:181], v[222:225], v[10:13]
	s_barrier
	s_add_u32 s6, s6, 0x40080
	s_addc_u32 s7, s7, 0
	s_add_i32 s18, s18, s10
	v_lshl_add_u64 v[158:159], s[6:7], 0, v[132:133]
	s_mov_b32 m0, s18
	s_nop 0
	global_load_lds_dwordx4 v[158:159], off
	v_lshl_add_u64 v[158:159], s[6:7], 0, v[136:137]
	s_add_i32 m0, s18, 0x2000
	s_nop 0
	global_load_lds_dwordx4 v[158:159], off
	s_waitcnt vmcnt(6)
	s_barrier
	v_mfma_f32_16x16x32_bf16 v[54:57], v[226:229], v[182:185], v[54:57]
	v_mfma_f32_16x16x32_bf16 v[50:53], v[234:237], v[182:185], v[50:53]
	v_mfma_f32_16x16x32_bf16 v[38:41], v[226:229], v[190:193], v[38:41]
	v_mfma_f32_16x16x32_bf16 v[34:37], v[234:237], v[190:193], v[34:37]
	v_mfma_f32_16x16x32_bf16 v[22:25], v[226:229], v[210:213], v[22:25]
	v_mfma_f32_16x16x32_bf16 v[18:21], v[234:237], v[210:213], v[18:21]
	v_mfma_f32_16x16x32_bf16 v[6:9], v[226:229], v[218:221], v[6:9]
	v_mfma_f32_16x16x32_bf16 v[2:5], v[234:237], v[218:221], v[2:5]
	v_mfma_f32_16x16x32_bf16 v[54:57], v[230:233], v[186:189], v[54:57]
	v_mfma_f32_16x16x32_bf16 v[50:53], v[238:241], v[186:189], v[50:53]
	v_mfma_f32_16x16x32_bf16 v[38:41], v[230:233], v[206:209], v[38:41]
	v_mfma_f32_16x16x32_bf16 v[34:37], v[238:241], v[206:209], v[34:37]
	v_mfma_f32_16x16x32_bf16 v[22:25], v[230:233], v[214:217], v[22:25]
	v_mfma_f32_16x16x32_bf16 v[18:21], v[238:241], v[214:217], v[18:21]
	v_mfma_f32_16x16x32_bf16 v[6:9], v[230:233], v[222:225], v[6:9]
	v_mfma_f32_16x16x32_bf16 v[2:5], v[238:241], v[222:225], v[2:5]
	s_add_i32 s20, s20, 2
	s_add_u32 s40, s40, 0x100
	s_addc_u32 s41, s41, 0
	s_add_u32 s5, s5, 0x100
	s_addc_u32 s17, s17, 0
	s_cmp_gt_u32 s20, 13
	s_barrier
	s_cbranch_scc0 .LBB0_246

.LBB0_491:
	s_ashr_i32 s43, s42, 31
	s_xor_b64 s[92:93], s[18:19], -1
	s_lshl_b64 s[14:15], s[42:43], 19
	s_add_u32 s16, s86, s14
	s_addc_u32 s17, s87, s15
	s_and_b64 s[14:15], s[18:19], exec
	s_cselect_b32 s26, s17, s77
	s_cselect_b32 s27, s16, s76
	s_ashr_i32 s5, s4, 31
	s_lshl_b64 s[14:15], s[4:5], 19
	s_add_u32 s14, s8, s14
	s_addc_u32 s15, s9, s15
	s_and_b64 s[18:19], s[18:19], exec
	s_cselect_b32 s5, s15, s1
	s_cselect_b32 s18, s14, s0
	s_add_u32 vcc_lo, s76, 0x40080
	s_addc_u32 vcc_hi, s77, 0
	s_add_u32 s19, s0, 0x100
	s_waitcnt lgkmcnt(0)
	s_addc_u32 s43, s1, 0
	s_mov_b32 s61, -2
	s_add_u32 s0, vcc_lo, 0xfffc0080
	s_addc_u32 s1, vcc_hi, -1
	s_add_i32 s28, s69, 0x100
	v_add_u32_e32 v0, s28, v151
	ds_read_b128 v[158:161], v0
	ds_read_b128 v[162:165], v0 offset:1024
	ds_read_b128 v[166:169], v0 offset:2048
	ds_read_b128 v[170:173], v0 offset:3072
	s_cmp_eq_u32 s61, 12
	s_cselect_b32 s77, s26, s1
	s_cselect_b32 s76, s27, s0
	s_cselect_b32 s1, s5, s43
	s_cselect_b32 s0, s18, s19
	v_lshl_add_u64 v[154:155], vcc, 0, v[140:141]
	s_add_i32 m0, s11, 0xc000
	ds_read_b128 v[174:177], v156
	ds_read_b128 v[178:181], v156 offset:1024
	ds_read_b128 v[182:185], v156 offset:2048
	ds_read_b128 v[186:189], v156 offset:3072
	ds_read_b128 v[190:193], v156 offset:4096
	ds_read_b128 v[206:209], v156 offset:5120
	ds_read_b128 v[210:213], v156 offset:6144
	ds_read_b128 v[214:217], v156 offset:7168
	global_load_lds_dwordx4 v[154:155], off
	v_lshl_add_u64 v[154:155], vcc, 0, v[142:143]
	s_add_i32 m0, s11, 0xe000
	s_nop 0
	global_load_lds_dwordx4 v[154:155], off
	s_waitcnt lgkmcnt(8)
	s_barrier
	s_waitcnt lgkmcnt(0)
	s_waitcnt lgkmcnt(0)
	v_mfma_f32_16x16x32_bf16 v[126:129], v[158:161], v[174:177], 0
	v_mfma_f32_16x16x32_bf16 v[122:125], v[166:169], v[174:177], 0
	v_mfma_f32_16x16x32_bf16 v[110:113], v[158:161], v[182:185], 0
	v_mfma_f32_16x16x32_bf16 v[106:109], v[166:169], v[182:185], 0
	v_mfma_f32_16x16x32_bf16 v[94:97], v[158:161], v[190:193], 0
	v_mfma_f32_16x16x32_bf16 v[90:93], v[166:169], v[190:193], 0
	v_mfma_f32_16x16x32_bf16 v[78:81], v[158:161], v[210:213], 0
	v_mfma_f32_16x16x32_bf16 v[74:77], v[166:169], v[210:213], 0
	v_mfma_f32_16x16x32_bf16 v[126:129], v[162:165], v[178:181], v[126:129]
	v_mfma_f32_16x16x32_bf16 v[122:125], v[170:173], v[178:181], v[122:125]
	v_mfma_f32_16x16x32_bf16 v[110:113], v[162:165], v[186:189], v[110:113]
	v_mfma_f32_16x16x32_bf16 v[106:109], v[170:173], v[186:189], v[106:109]
	v_mfma_f32_16x16x32_bf16 v[94:97], v[162:165], v[206:209], v[94:97]
	v_mfma_f32_16x16x32_bf16 v[90:93], v[170:173], v[206:209], v[90:93]
	v_mfma_f32_16x16x32_bf16 v[78:81], v[162:165], v[214:217], v[78:81]
	v_mfma_f32_16x16x32_bf16 v[74:77], v[170:173], v[214:217], v[74:77]
	s_barrier
	s_add_i32 s63, s96, 0x100
	s_add_i32 s28, s28, s3
	v_add_u32_e32 v0, s63, v151
	v_lshl_add_u64 v[154:155], s[0:1], 0, v[132:133]
	s_mov_b32 m0, s28
	ds_read_b128 v[218:221], v0
	ds_read_b128 v[222:225], v0 offset:1024
	ds_read_b128 v[226:229], v0 offset:2048
	ds_read_b128 v[230:233], v0 offset:3072
	global_load_lds_dwordx4 v[154:155], off
	v_lshl_add_u64 v[234:235], s[0:1], 0, v[136:137]
	s_add_i32 m0, s28, 0x2000
	s_nop 0
	global_load_lds_dwordx4 v[234:235], off
	s_barrier
	s_waitcnt lgkmcnt(0)
	s_waitcnt lgkmcnt(0)
	v_mfma_f32_16x16x32_bf16 v[118:121], v[218:221], v[174:177], 0
	v_mfma_f32_16x16x32_bf16 v[114:117], v[226:229], v[174:177], 0
	v_mfma_f32_16x16x32_bf16 v[102:105], v[218:221], v[182:185], 0
	v_mfma_f32_16x16x32_bf16 v[98:101], v[226:229], v[182:185], 0
	v_mfma_f32_16x16x32_bf16 v[86:89], v[218:221], v[190:193], 0
	v_mfma_f32_16x16x32_bf16 v[82:85], v[226:229], v[190:193], 0
	v_mfma_f32_16x16x32_bf16 v[70:73], v[218:221], v[210:213], 0
	v_mfma_f32_16x16x32_bf16 v[66:69], v[226:229], v[210:213], 0
	v_mfma_f32_16x16x32_bf16 v[118:121], v[222:225], v[178:181], v[118:121]
	v_mfma_f32_16x16x32_bf16 v[114:117], v[230:233], v[178:181], v[114:117]
	v_mfma_f32_16x16x32_bf16 v[102:105], v[222:225], v[186:189], v[102:105]
	v_mfma_f32_16x16x32_bf16 v[98:101], v[230:233], v[186:189], v[98:101]
	v_mfma_f32_16x16x32_bf16 v[86:89], v[222:225], v[206:209], v[86:89]
	v_mfma_f32_16x16x32_bf16 v[82:85], v[230:233], v[206:209], v[82:85]
	v_mfma_f32_16x16x32_bf16 v[70:73], v[222:225], v[214:217], v[70:73]
	v_mfma_f32_16x16x32_bf16 v[66:69], v[230:233], v[214:217], v[66:69]
	s_mov_b32 m0, s11
	v_lshl_add_u64 v[236:237], s[76:77], 0, v[130:131]
	s_barrier
	ds_read_b128 v[174:177], v156 offset:16384
	ds_read_b128 v[178:181], v156 offset:17408
	ds_read_b128 v[182:185], v156 offset:18432
	ds_read_b128 v[186:189], v156 offset:19456
	ds_read_b128 v[190:193], v156 offset:20480
	ds_read_b128 v[206:209], v156 offset:21504
	ds_read_b128 v[210:213], v156 offset:22528
	ds_read_b128 v[214:217], v156 offset:23552
	global_load_lds_dwordx4 v[236:237], off
	v_lshl_add_u64 v[238:239], s[76:77], 0, v[134:135]
	s_mov_b32 m0, s12
	s_nop 0
	global_load_lds_dwordx4 v[238:239], off
	s_barrier
	s_waitcnt lgkmcnt(0)
	s_waitcnt lgkmcnt(0)
	v_mfma_f32_16x16x32_bf16 v[62:65], v[158:161], v[174:177], 0
	v_mfma_f32_16x16x32_bf16 v[58:61], v[166:169], v[174:177], 0
	v_mfma_f32_16x16x32_bf16 v[46:49], v[158:161], v[182:185], 0
	v_mfma_f32_16x16x32_bf16 v[42:45], v[166:169], v[182:185], 0
	v_mfma_f32_16x16x32_bf16 v[30:33], v[158:161], v[190:193], 0
	v_mfma_f32_16x16x32_bf16 v[26:29], v[166:169], v[190:193], 0
	v_mfma_f32_16x16x32_bf16 v[14:17], v[158:161], v[210:213], 0
	v_mfma_f32_16x16x32_bf16 v[10:13], v[166:169], v[210:213], 0
	v_mfma_f32_16x16x32_bf16 v[62:65], v[162:165], v[178:181], v[62:65]
	v_mfma_f32_16x16x32_bf16 v[58:61], v[170:173], v[178:181], v[58:61]
	v_mfma_f32_16x16x32_bf16 v[46:49], v[162:165], v[186:189], v[46:49]
	v_mfma_f32_16x16x32_bf16 v[42:45], v[170:173], v[186:189], v[42:45]
	v_mfma_f32_16x16x32_bf16 v[30:33], v[162:165], v[206:209], v[30:33]
	v_mfma_f32_16x16x32_bf16 v[26:29], v[170:173], v[206:209], v[26:29]
	v_mfma_f32_16x16x32_bf16 v[14:17], v[162:165], v[214:217], v[14:17]
	v_mfma_f32_16x16x32_bf16 v[10:13], v[170:173], v[214:217], v[10:13]
	s_barrier
	s_add_u32 s28, s0, 0x40000
	s_addc_u32 s29, s1, 0
	s_add_i32 s63, s63, s3
	v_lshl_add_u64 v[158:159], s[28:29], 0, v[132:133]
	s_mov_b32 m0, s63
	s_nop 0
	global_load_lds_dwordx4 v[158:159], off
	v_lshl_add_u64 v[158:159], s[28:29], 0, v[136:137]
	s_add_i32 m0, s63, 0x2000
	s_nop 0
	global_load_lds_dwordx4 v[158:159], off
	s_waitcnt vmcnt(6)
	s_barrier
	v_mfma_f32_16x16x32_bf16 v[54:57], v[218:221], v[174:177], 0
	v_mfma_f32_16x16x32_bf16 v[50:53], v[226:229], v[174:177], 0
	v_mfma_f32_16x16x32_bf16 v[38:41], v[218:221], v[182:185], 0
	v_mfma_f32_16x16x32_bf16 v[34:37], v[226:229], v[182:185], 0
	v_mfma_f32_16x16x32_bf16 v[22:25], v[218:221], v[190:193], 0
	v_mfma_f32_16x16x32_bf16 v[18:21], v[226:229], v[190:193], 0
	v_mfma_f32_16x16x32_bf16 v[6:9], v[218:221], v[210:213], 0
	v_mfma_f32_16x16x32_bf16 v[2:5], v[226:229], v[210:213], 0
	v_mfma_f32_16x16x32_bf16 v[54:57], v[222:225], v[178:181], v[54:57]
	v_mfma_f32_16x16x32_bf16 v[50:53], v[230:233], v[178:181], v[50:53]
	v_mfma_f32_16x16x32_bf16 v[38:41], v[222:225], v[186:189], v[38:41]
	v_mfma_f32_16x16x32_bf16 v[34:37], v[230:233], v[186:189], v[34:37]
	v_mfma_f32_16x16x32_bf16 v[22:25], v[222:225], v[206:209], v[22:25]
	v_mfma_f32_16x16x32_bf16 v[18:21], v[230:233], v[206:209], v[18:21]
	v_mfma_f32_16x16x32_bf16 v[6:9], v[222:225], v[214:217], v[6:9]
	v_mfma_f32_16x16x32_bf16 v[2:5], v[230:233], v[214:217], v[2:5]
	s_add_i32 s63, s97, 0x100
	v_add_u32_e32 v0, s63, v151
	s_barrier
	ds_read_b128 v[158:161], v0
	ds_read_b128 v[162:165], v0 offset:1024
	ds_read_b128 v[166:169], v0 offset:2048
	ds_read_b128 v[170:173], v0 offset:3072
	s_add_u32 s28, s76, 0x40000
	s_addc_u32 s29, s77, 0
	s_mov_b32 m0, s13
	v_lshl_add_u64 v[218:219], s[28:29], 0, v[130:131]
	ds_read_b128 v[174:177], v156 offset:32768
	ds_read_b128 v[178:181], v156 offset:33792
	ds_read_b128 v[182:185], v156 offset:34816
	ds_read_b128 v[186:189], v156 offset:35840
	ds_read_b128 v[190:193], v156 offset:36864
	ds_read_b128 v[206:209], v156 offset:37888
	ds_read_b128 v[210:213], v156 offset:38912
	ds_read_b128 v[214:217], v156 offset:39936
	global_load_lds_dwordx4 v[218:219], off
	v_lshl_add_u64 v[218:219], s[28:29], 0, v[134:135]
	s_mov_b32 m0, s20
	s_nop 0
	global_load_lds_dwordx4 v[218:219], off
	s_waitcnt lgkmcnt(8)
	s_barrier
	s_waitcnt lgkmcnt(0)
	s_waitcnt lgkmcnt(0)
	v_mfma_f32_16x16x32_bf16 v[126:129], v[158:161], v[174:177], v[126:129]
	v_mfma_f32_16x16x32_bf16 v[122:125], v[166:169], v[174:177], v[122:125]
	v_mfma_f32_16x16x32_bf16 v[110:113], v[158:161], v[182:185], v[110:113]
	v_mfma_f32_16x16x32_bf16 v[106:109], v[166:169], v[182:185], v[106:109]
	v_mfma_f32_16x16x32_bf16 v[94:97], v[158:161], v[190:193], v[94:97]
	v_mfma_f32_16x16x32_bf16 v[90:93], v[166:169], v[190:193], v[90:93]
	v_mfma_f32_16x16x32_bf16 v[78:81], v[158:161], v[210:213], v[78:81]
	v_mfma_f32_16x16x32_bf16 v[74:77], v[166:169], v[210:213], v[74:77]
	v_mfma_f32_16x16x32_bf16 v[126:129], v[162:165], v[178:181], v[126:129]
	v_mfma_f32_16x16x32_bf16 v[122:125], v[170:173], v[178:181], v[122:125]
	v_mfma_f32_16x16x32_bf16 v[110:113], v[162:165], v[186:189], v[110:113]
	v_mfma_f32_16x16x32_bf16 v[106:109], v[170:173], v[186:189], v[106:109]
	v_mfma_f32_16x16x32_bf16 v[94:97], v[162:165], v[206:209], v[94:97]
	v_mfma_f32_16x16x32_bf16 v[90:93], v[170:173], v[206:209], v[90:93]
	v_mfma_f32_16x16x32_bf16 v[78:81], v[162:165], v[214:217], v[78:81]
	v_mfma_f32_16x16x32_bf16 v[74:77], v[170:173], v[214:217], v[74:77]
	s_barrier
	s_add_i32 s28, s44, 0x100
	s_add_i32 s29, s63, s3
	v_add_u32_e32 v0, s28, v151
	v_lshl_add_u64 v[154:155], v[154:155], 0, s[46:47]
	s_mov_b32 m0, s29
	ds_read_b128 v[218:221], v0
	ds_read_b128 v[222:225], v0 offset:1024
	ds_read_b128 v[226:229], v0 offset:2048
	ds_read_b128 v[230:233], v0 offset:3072
	global_load_lds_dwordx4 v[154:155], off
	v_lshl_add_u64 v[154:155], v[234:235], 0, s[46:47]
	s_add_i32 m0, s29, 0x2000
	s_nop 0
	global_load_lds_dwordx4 v[154:155], off
	s_barrier
	s_waitcnt lgkmcnt(0)
	s_waitcnt lgkmcnt(0)
	v_mfma_f32_16x16x32_bf16 v[118:121], v[218:221], v[174:177], v[118:121]
	v_mfma_f32_16x16x32_bf16 v[114:117], v[226:229], v[174:177], v[114:117]
	v_mfma_f32_16x16x32_bf16 v[102:105], v[218:221], v[182:185], v[102:105]
	v_mfma_f32_16x16x32_bf16 v[98:101], v[226:229], v[182:185], v[98:101]
	v_mfma_f32_16x16x32_bf16 v[86:89], v[218:221], v[190:193], v[86:89]
	v_mfma_f32_16x16x32_bf16 v[82:85], v[226:229], v[190:193], v[82:85]
	v_mfma_f32_16x16x32_bf16 v[70:73], v[218:221], v[210:213], v[70:73]
	v_mfma_f32_16x16x32_bf16 v[66:69], v[226:229], v[210:213], v[66:69]
	v_mfma_f32_16x16x32_bf16 v[118:121], v[222:225], v[178:181], v[118:121]
	v_mfma_f32_16x16x32_bf16 v[114:117], v[230:233], v[178:181], v[114:117]
	v_mfma_f32_16x16x32_bf16 v[102:105], v[222:225], v[186:189], v[102:105]
	v_mfma_f32_16x16x32_bf16 v[98:101], v[230:233], v[186:189], v[98:101]
	v_mfma_f32_16x16x32_bf16 v[86:89], v[222:225], v[206:209], v[86:89]
	v_mfma_f32_16x16x32_bf16 v[82:85], v[230:233], v[206:209], v[82:85]
	v_mfma_f32_16x16x32_bf16 v[70:73], v[222:225], v[214:217], v[70:73]
	v_mfma_f32_16x16x32_bf16 v[66:69], v[230:233], v[214:217], v[66:69]
	s_mov_b32 m0, s23
	v_lshl_add_u64 v[154:155], v[236:237], 0, s[46:47]
	s_barrier
	ds_read_b128 v[174:177], v156 offset:49152
	ds_read_b128 v[178:181], v156 offset:50176
	ds_read_b128 v[182:185], v156 offset:51200
	ds_read_b128 v[186:189], v156 offset:52224
	ds_read_b128 v[190:193], v156 offset:53248
	ds_read_b128 v[206:209], v156 offset:54272
	ds_read_b128 v[210:213], v156 offset:55296
	ds_read_b128 v[214:217], v156 offset:56320
	global_load_lds_dwordx4 v[154:155], off
	v_lshl_add_u64 v[154:155], v[238:239], 0, s[46:47]
	s_mov_b32 m0, s24
	s_nop 0
	global_load_lds_dwordx4 v[154:155], off
	s_barrier
	s_waitcnt lgkmcnt(0)
	s_waitcnt lgkmcnt(0)
	v_mfma_f32_16x16x32_bf16 v[62:65], v[158:161], v[174:177], v[62:65]
	v_mfma_f32_16x16x32_bf16 v[58:61], v[166:169], v[174:177], v[58:61]
	v_mfma_f32_16x16x32_bf16 v[46:49], v[158:161], v[182:185], v[46:49]
	v_mfma_f32_16x16x32_bf16 v[42:45], v[166:169], v[182:185], v[42:45]
	v_mfma_f32_16x16x32_bf16 v[30:33], v[158:161], v[190:193], v[30:33]
	v_mfma_f32_16x16x32_bf16 v[26:29], v[166:169], v[190:193], v[26:29]
	v_mfma_f32_16x16x32_bf16 v[14:17], v[158:161], v[210:213], v[14:17]
	v_mfma_f32_16x16x32_bf16 v[10:13], v[166:169], v[210:213], v[10:13]
	v_mfma_f32_16x16x32_bf16 v[62:65], v[162:165], v[178:181], v[62:65]
	v_mfma_f32_16x16x32_bf16 v[58:61], v[170:173], v[178:181], v[58:61]
	v_mfma_f32_16x16x32_bf16 v[46:49], v[162:165], v[186:189], v[46:49]
	v_mfma_f32_16x16x32_bf16 v[42:45], v[170:173], v[186:189], v[42:45]
	v_mfma_f32_16x16x32_bf16 v[30:33], v[162:165], v[206:209], v[30:33]
	v_mfma_f32_16x16x32_bf16 v[26:29], v[170:173], v[206:209], v[26:29]
	v_mfma_f32_16x16x32_bf16 v[14:17], v[162:165], v[214:217], v[14:17]
	v_mfma_f32_16x16x32_bf16 v[10:13], v[170:173], v[214:217], v[10:13]
	s_barrier
	s_add_u32 s0, s0, 0x40080
	s_addc_u32 s1, s1, 0
	s_add_i32 s28, s28, s3
	v_lshl_add_u64 v[154:155], s[0:1], 0, v[132:133]
	s_mov_b32 m0, s28
	s_nop 0
	global_load_lds_dwordx4 v[154:155], off
	v_lshl_add_u64 v[154:155], s[0:1], 0, v[136:137]
	s_add_i32 m0, s28, 0x2000
	s_nop 0
	global_load_lds_dwordx4 v[154:155], off
	s_waitcnt vmcnt(6)
	s_barrier
	v_mfma_f32_16x16x32_bf16 v[54:57], v[218:221], v[174:177], v[54:57]
	v_mfma_f32_16x16x32_bf16 v[50:53], v[226:229], v[174:177], v[50:53]
	v_mfma_f32_16x16x32_bf16 v[38:41], v[218:221], v[182:185], v[38:41]
	v_mfma_f32_16x16x32_bf16 v[34:37], v[226:229], v[182:185], v[34:37]
	v_mfma_f32_16x16x32_bf16 v[22:25], v[218:221], v[190:193], v[22:25]
	v_mfma_f32_16x16x32_bf16 v[18:21], v[226:229], v[190:193], v[18:21]
	v_mfma_f32_16x16x32_bf16 v[6:9], v[218:221], v[210:213], v[6:9]
	v_mfma_f32_16x16x32_bf16 v[2:5], v[226:229], v[210:213], v[2:5]
	v_mfma_f32_16x16x32_bf16 v[54:57], v[222:225], v[178:181], v[54:57]
	v_mfma_f32_16x16x32_bf16 v[50:53], v[230:233], v[178:181], v[50:53]
	v_mfma_f32_16x16x32_bf16 v[38:41], v[222:225], v[186:189], v[38:41]
	v_mfma_f32_16x16x32_bf16 v[34:37], v[230:233], v[186:189], v[34:37]
	v_mfma_f32_16x16x32_bf16 v[22:25], v[222:225], v[206:209], v[22:25]
	v_mfma_f32_16x16x32_bf16 v[18:21], v[230:233], v[206:209], v[18:21]
	v_mfma_f32_16x16x32_bf16 v[6:9], v[222:225], v[214:217], v[6:9]
	v_mfma_f32_16x16x32_bf16 v[2:5], v[230:233], v[214:217], v[2:5]
	s_add_i32 s61, s61, 2
	s_add_u32 vcc_lo, vcc_lo, 0x100
	s_addc_u32 vcc_hi, vcc_hi, 0
	s_add_u32 s19, s19, 0x100
	s_addc_u32 s43, s43, 0
	s_cmp_gt_u32 s61, 13
	s_barrier
	s_cbranch_scc1 .Lmy_kexit1
.LBB0_492:
	s_add_u32 s0, vcc_lo, 0xfffc0080
	s_addc_u32 s1, vcc_hi, -1
	s_add_i32 s28, s69, 0x100
	v_add_u32_e32 v0, s28, v151
	ds_read_b128 v[158:161], v0
	ds_read_b128 v[162:165], v0 offset:1024
	ds_read_b128 v[166:169], v0 offset:2048
	ds_read_b128 v[170:173], v0 offset:3072
	s_cmp_eq_u32 s61, 12
	s_cselect_b32 s77, s26, s1
	s_cselect_b32 s76, s27, s0
	s_cselect_b32 s1, s5, s43
	s_cselect_b32 s0, s18, s19
	v_lshl_add_u64 v[154:155], vcc, 0, v[140:141]
	s_add_i32 m0, s11, 0xc000
	ds_read_b128 v[174:177], v156
	ds_read_b128 v[178:181], v156 offset:1024
	ds_read_b128 v[182:185], v156 offset:2048
	ds_read_b128 v[186:189], v156 offset:3072
	ds_read_b128 v[190:193], v156 offset:4096
	ds_read_b128 v[206:209], v156 offset:5120
	ds_read_b128 v[210:213], v156 offset:6144
	ds_read_b128 v[214:217], v156 offset:7168
	global_load_lds_dwordx4 v[154:155], off
	v_lshl_add_u64 v[154:155], vcc, 0, v[142:143]
	s_add_i32 m0, s11, 0xe000
	s_nop 0
	global_load_lds_dwordx4 v[154:155], off
	s_waitcnt lgkmcnt(8)
	s_barrier
	s_waitcnt lgkmcnt(0)
	s_waitcnt lgkmcnt(0)
	v_mfma_f32_16x16x32_bf16 v[126:129], v[158:161], v[174:177], v[126:129]
	v_mfma_f32_16x16x32_bf16 v[122:125], v[166:169], v[174:177], v[122:125]
	v_mfma_f32_16x16x32_bf16 v[110:113], v[158:161], v[182:185], v[110:113]
	v_mfma_f32_16x16x32_bf16 v[106:109], v[166:169], v[182:185], v[106:109]
	v_mfma_f32_16x16x32_bf16 v[94:97], v[158:161], v[190:193], v[94:97]
	v_mfma_f32_16x16x32_bf16 v[90:93], v[166:169], v[190:193], v[90:93]
	v_mfma_f32_16x16x32_bf16 v[78:81], v[158:161], v[210:213], v[78:81]
	v_mfma_f32_16x16x32_bf16 v[74:77], v[166:169], v[210:213], v[74:77]
	v_mfma_f32_16x16x32_bf16 v[126:129], v[162:165], v[178:181], v[126:129]
	v_mfma_f32_16x16x32_bf16 v[122:125], v[170:173], v[178:181], v[122:125]
	v_mfma_f32_16x16x32_bf16 v[110:113], v[162:165], v[186:189], v[110:113]
	v_mfma_f32_16x16x32_bf16 v[106:109], v[170:173], v[186:189], v[106:109]
	v_mfma_f32_16x16x32_bf16 v[94:97], v[162:165], v[206:209], v[94:97]
	v_mfma_f32_16x16x32_bf16 v[90:93], v[170:173], v[206:209], v[90:93]
	v_mfma_f32_16x16x32_bf16 v[78:81], v[162:165], v[214:217], v[78:81]
	v_mfma_f32_16x16x32_bf16 v[74:77], v[170:173], v[214:217], v[74:77]
	s_barrier
	s_add_i32 s63, s96, 0x100
	s_add_i32 s28, s28, s3
	v_add_u32_e32 v0, s63, v151
	v_lshl_add_u64 v[154:155], s[0:1], 0, v[132:133]
	s_mov_b32 m0, s28
	ds_read_b128 v[218:221], v0
	ds_read_b128 v[222:225], v0 offset:1024
	ds_read_b128 v[226:229], v0 offset:2048
	ds_read_b128 v[230:233], v0 offset:3072
	global_load_lds_dwordx4 v[154:155], off
	v_lshl_add_u64 v[234:235], s[0:1], 0, v[136:137]
	s_add_i32 m0, s28, 0x2000
	s_nop 0
	global_load_lds_dwordx4 v[234:235], off
	s_barrier
	s_waitcnt lgkmcnt(0)
	s_waitcnt lgkmcnt(0)
	v_mfma_f32_16x16x32_bf16 v[118:121], v[218:221], v[174:177], v[118:121]
	v_mfma_f32_16x16x32_bf16 v[114:117], v[226:229], v[174:177], v[114:117]
	v_mfma_f32_16x16x32_bf16 v[102:105], v[218:221], v[182:185], v[102:105]
	v_mfma_f32_16x16x32_bf16 v[98:101], v[226:229], v[182:185], v[98:101]
	v_mfma_f32_16x16x32_bf16 v[86:89], v[218:221], v[190:193], v[86:89]
	v_mfma_f32_16x16x32_bf16 v[82:85], v[226:229], v[190:193], v[82:85]
	v_mfma_f32_16x16x32_bf16 v[70:73], v[218:221], v[210:213], v[70:73]
	v_mfma_f32_16x16x32_bf16 v[66:69], v[226:229], v[210:213], v[66:69]
	v_mfma_f32_16x16x32_bf16 v[118:121], v[222:225], v[178:181], v[118:121]
	v_mfma_f32_16x16x32_bf16 v[114:117], v[230:233], v[178:181], v[114:117]
	v_mfma_f32_16x16x32_bf16 v[102:105], v[222:225], v[186:189], v[102:105]
	v_mfma_f32_16x16x32_bf16 v[98:101], v[230:233], v[186:189], v[98:101]
	v_mfma_f32_16x16x32_bf16 v[86:89], v[222:225], v[206:209], v[86:89]
	v_mfma_f32_16x16x32_bf16 v[82:85], v[230:233], v[206:209], v[82:85]
	v_mfma_f32_16x16x32_bf16 v[70:73], v[222:225], v[214:217], v[70:73]
	v_mfma_f32_16x16x32_bf16 v[66:69], v[230:233], v[214:217], v[66:69]
	s_mov_b32 m0, s11
	v_lshl_add_u64 v[236:237], s[76:77], 0, v[130:131]
	s_barrier
	ds_read_b128 v[174:177], v156 offset:16384
	ds_read_b128 v[178:181], v156 offset:17408
	ds_read_b128 v[182:185], v156 offset:18432
	ds_read_b128 v[186:189], v156 offset:19456
	ds_read_b128 v[190:193], v156 offset:20480
	ds_read_b128 v[206:209], v156 offset:21504
	ds_read_b128 v[210:213], v156 offset:22528
	ds_read_b128 v[214:217], v156 offset:23552
	global_load_lds_dwordx4 v[236:237], off
	v_lshl_add_u64 v[238:239], s[76:77], 0, v[134:135]
	s_mov_b32 m0, s12
	s_nop 0
	global_load_lds_dwordx4 v[238:239], off
	s_barrier
	s_waitcnt lgkmcnt(0)
	s_waitcnt lgkmcnt(0)
	v_mfma_f32_16x16x32_bf16 v[62:65], v[158:161], v[174:177], v[62:65]
	v_mfma_f32_16x16x32_bf16 v[58:61], v[166:169], v[174:177], v[58:61]
	v_mfma_f32_16x16x32_bf16 v[46:49], v[158:161], v[182:185], v[46:49]
	v_mfma_f32_16x16x32_bf16 v[42:45], v[166:169], v[182:185], v[42:45]
	v_mfma_f32_16x16x32_bf16 v[30:33], v[158:161], v[190:193], v[30:33]
	v_mfma_f32_16x16x32_bf16 v[26:29], v[166:169], v[190:193], v[26:29]
	v_mfma_f32_16x16x32_bf16 v[14:17], v[158:161], v[210:213], v[14:17]
	v_mfma_f32_16x16x32_bf16 v[10:13], v[166:169], v[210:213], v[10:13]
	v_mfma_f32_16x16x32_bf16 v[62:65], v[162:165], v[178:181], v[62:65]
	v_mfma_f32_16x16x32_bf16 v[58:61], v[170:173], v[178:181], v[58:61]
	v_mfma_f32_16x16x32_bf16 v[46:49], v[162:165], v[186:189], v[46:49]
	v_mfma_f32_16x16x32_bf16 v[42:45], v[170:173], v[186:189], v[42:45]
	v_mfma_f32_16x16x32_bf16 v[30:33], v[162:165], v[206:209], v[30:33]
	v_mfma_f32_16x16x32_bf16 v[26:29], v[170:173], v[206:209], v[26:29]
	v_mfma_f32_16x16x32_bf16 v[14:17], v[162:165], v[214:217], v[14:17]
	v_mfma_f32_16x16x32_bf16 v[10:13], v[170:173], v[214:217], v[10:13]
	s_barrier
	s_add_u32 s28, s0, 0x40000
	s_addc_u32 s29, s1, 0
	s_add_i32 s63, s63, s3
	v_lshl_add_u64 v[158:159], s[28:29], 0, v[132:133]
	s_mov_b32 m0, s63
	s_nop 0
	global_load_lds_dwordx4 v[158:159], off
	v_lshl_add_u64 v[158:159], s[28:29], 0, v[136:137]
	s_add_i32 m0, s63, 0x2000
	s_nop 0
	global_load_lds_dwordx4 v[158:159], off
	s_waitcnt vmcnt(6)
	s_barrier
	v_mfma_f32_16x16x32_bf16 v[54:57], v[218:221], v[174:177], v[54:57]
	v_mfma_f32_16x16x32_bf16 v[50:53], v[226:229], v[174:177], v[50:53]
	v_mfma_f32_16x16x32_bf16 v[38:41], v[218:221], v[182:185], v[38:41]
	v_mfma_f32_16x16x32_bf16 v[34:37], v[226:229], v[182:185], v[34:37]
	v_mfma_f32_16x16x32_bf16 v[22:25], v[218:221], v[190:193], v[22:25]
	v_mfma_f32_16x16x32_bf16 v[18:21], v[226:229], v[190:193], v[18:21]
	v_mfma_f32_16x16x32_bf16 v[6:9], v[218:221], v[210:213], v[6:9]
	v_mfma_f32_16x16x32_bf16 v[2:5], v[226:229], v[210:213], v[2:5]
	v_mfma_f32_16x16x32_bf16 v[54:57], v[222:225], v[178:181], v[54:57]
	v_mfma_f32_16x16x32_bf16 v[50:53], v[230:233], v[178:181], v[50:53]
	v_mfma_f32_16x16x32_bf16 v[38:41], v[222:225], v[186:189], v[38:41]
	v_mfma_f32_16x16x32_bf16 v[34:37], v[230:233], v[186:189], v[34:37]
	v_mfma_f32_16x16x32_bf16 v[22:25], v[222:225], v[206:209], v[22:25]
	v_mfma_f32_16x16x32_bf16 v[18:21], v[230:233], v[206:209], v[18:21]
	v_mfma_f32_16x16x32_bf16 v[6:9], v[222:225], v[214:217], v[6:9]
	v_mfma_f32_16x16x32_bf16 v[2:5], v[230:233], v[214:217], v[2:5]
	s_add_i32 s63, s97, 0x100
	v_add_u32_e32 v0, s63, v151
	s_barrier
	ds_read_b128 v[158:161], v0
	ds_read_b128 v[162:165], v0 offset:1024
	ds_read_b128 v[166:169], v0 offset:2048
	ds_read_b128 v[170:173], v0 offset:3072
	s_add_u32 s28, s76, 0x40000
	s_addc_u32 s29, s77, 0
	s_mov_b32 m0, s13
	v_lshl_add_u64 v[218:219], s[28:29], 0, v[130:131]
	ds_read_b128 v[174:177], v156 offset:32768
	ds_read_b128 v[178:181], v156 offset:33792
	ds_read_b128 v[182:185], v156 offset:34816
	ds_read_b128 v[186:189], v156 offset:35840
	ds_read_b128 v[190:193], v156 offset:36864
	ds_read_b128 v[206:209], v156 offset:37888
	ds_read_b128 v[210:213], v156 offset:38912
	ds_read_b128 v[214:217], v156 offset:39936
	global_load_lds_dwordx4 v[218:219], off
	v_lshl_add_u64 v[218:219], s[28:29], 0, v[134:135]
	s_mov_b32 m0, s20
	s_nop 0
	global_load_lds_dwordx4 v[218:219], off
	s_waitcnt lgkmcnt(8)
	s_barrier
	s_waitcnt lgkmcnt(0)
	s_waitcnt lgkmcnt(0)
	v_mfma_f32_16x16x32_bf16 v[126:129], v[158:161], v[174:177], v[126:129]
	v_mfma_f32_16x16x32_bf16 v[122:125], v[166:169], v[174:177], v[122:125]
	v_mfma_f32_16x16x32_bf16 v[110:113], v[158:161], v[182:185], v[110:113]
	v_mfma_f32_16x16x32_bf16 v[106:109], v[166:169], v[182:185], v[106:109]
	v_mfma_f32_16x16x32_bf16 v[94:97], v[158:161], v[190:193], v[94:97]
	v_mfma_f32_16x16x32_bf16 v[90:93], v[166:169], v[190:193], v[90:93]
	v_mfma_f32_16x16x32_bf16 v[78:81], v[158:161], v[210:213], v[78:81]
	v_mfma_f32_16x16x32_bf16 v[74:77], v[166:169], v[210:213], v[74:77]
	v_mfma_f32_16x16x32_bf16 v[126:129], v[162:165], v[178:181], v[126:129]
	v_mfma_f32_16x16x32_bf16 v[122:125], v[170:173], v[178:181], v[122:125]
	v_mfma_f32_16x16x32_bf16 v[110:113], v[162:165], v[186:189], v[110:113]
	v_mfma_f32_16x16x32_bf16 v[106:109], v[170:173], v[186:189], v[106:109]
	v_mfma_f32_16x16x32_bf16 v[94:97], v[162:165], v[206:209], v[94:97]
	v_mfma_f32_16x16x32_bf16 v[90:93], v[170:173], v[206:209], v[90:93]
	v_mfma_f32_16x16x32_bf16 v[78:81], v[162:165], v[214:217], v[78:81]
	v_mfma_f32_16x16x32_bf16 v[74:77], v[170:173], v[214:217], v[74:77]
	s_barrier
	s_add_i32 s28, s44, 0x100
	s_add_i32 s29, s63, s3
	v_add_u32_e32 v0, s28, v151
	v_lshl_add_u64 v[154:155], v[154:155], 0, s[46:47]
	s_mov_b32 m0, s29
	ds_read_b128 v[218:221], v0
	ds_read_b128 v[222:225], v0 offset:1024
	ds_read_b128 v[226:229], v0 offset:2048
	ds_read_b128 v[230:233], v0 offset:3072
	global_load_lds_dwordx4 v[154:155], off
	v_lshl_add_u64 v[154:155], v[234:235], 0, s[46:47]
	s_add_i32 m0, s29, 0x2000
	s_nop 0
	global_load_lds_dwordx4 v[154:155], off
	s_barrier
	s_waitcnt lgkmcnt(0)
	s_waitcnt lgkmcnt(0)
	v_mfma_f32_16x16x32_bf16 v[118:121], v[218:221], v[174:177], v[118:121]
	v_mfma_f32_16x16x32_bf16 v[114:117], v[226:229], v[174:177], v[114:117]
	v_mfma_f32_16x16x32_bf16 v[102:105], v[218:221], v[182:185], v[102:105]
	v_mfma_f32_16x16x32_bf16 v[98:101], v[226:229], v[182:185], v[98:101]
	v_mfma_f32_16x16x32_bf16 v[86:89], v[218:221], v[190:193], v[86:89]
	v_mfma_f32_16x16x32_bf16 v[82:85], v[226:229], v[190:193], v[82:85]
	v_mfma_f32_16x16x32_bf16 v[70:73], v[218:221], v[210:213], v[70:73]
	v_mfma_f32_16x16x32_bf16 v[66:69], v[226:229], v[210:213], v[66:69]
	v_mfma_f32_16x16x32_bf16 v[118:121], v[222:225], v[178:181], v[118:121]
	v_mfma_f32_16x16x32_bf16 v[114:117], v[230:233], v[178:181], v[114:117]
	v_mfma_f32_16x16x32_bf16 v[102:105], v[222:225], v[186:189], v[102:105]
	v_mfma_f32_16x16x32_bf16 v[98:101], v[230:233], v[186:189], v[98:101]
	v_mfma_f32_16x16x32_bf16 v[86:89], v[222:225], v[206:209], v[86:89]
	v_mfma_f32_16x16x32_bf16 v[82:85], v[230:233], v[206:209], v[82:85]
	v_mfma_f32_16x16x32_bf16 v[70:73], v[222:225], v[214:217], v[70:73]
	v_mfma_f32_16x16x32_bf16 v[66:69], v[230:233], v[214:217], v[66:69]
	s_mov_b32 m0, s23
	v_lshl_add_u64 v[154:155], v[236:237], 0, s[46:47]
	s_barrier
	ds_read_b128 v[174:177], v156 offset:49152
	ds_read_b128 v[178:181], v156 offset:50176
	ds_read_b128 v[182:185], v156 offset:51200
	ds_read_b128 v[186:189], v156 offset:52224
	ds_read_b128 v[190:193], v156 offset:53248
	ds_read_b128 v[206:209], v156 offset:54272
	ds_read_b128 v[210:213], v156 offset:55296
	ds_read_b128 v[214:217], v156 offset:56320
	global_load_lds_dwordx4 v[154:155], off
	v_lshl_add_u64 v[154:155], v[238:239], 0, s[46:47]
	s_mov_b32 m0, s24
	s_nop 0
	global_load_lds_dwordx4 v[154:155], off
	s_barrier
	s_waitcnt lgkmcnt(0)
	s_waitcnt lgkmcnt(0)
	v_mfma_f32_16x16x32_bf16 v[62:65], v[158:161], v[174:177], v[62:65]
	v_mfma_f32_16x16x32_bf16 v[58:61], v[166:169], v[174:177], v[58:61]
	v_mfma_f32_16x16x32_bf16 v[46:49], v[158:161], v[182:185], v[46:49]
	v_mfma_f32_16x16x32_bf16 v[42:45], v[166:169], v[182:185], v[42:45]
	v_mfma_f32_16x16x32_bf16 v[30:33], v[158:161], v[190:193], v[30:33]
	v_mfma_f32_16x16x32_bf16 v[26:29], v[166:169], v[190:193], v[26:29]
	v_mfma_f32_16x16x32_bf16 v[14:17], v[158:161], v[210:213], v[14:17]
	v_mfma_f32_16x16x32_bf16 v[10:13], v[166:169], v[210:213], v[10:13]
	v_mfma_f32_16x16x32_bf16 v[62:65], v[162:165], v[178:181], v[62:65]
	v_mfma_f32_16x16x32_bf16 v[58:61], v[170:173], v[178:181], v[58:61]
	v_mfma_f32_16x16x32_bf16 v[46:49], v[162:165], v[186:189], v[46:49]
	v_mfma_f32_16x16x32_bf16 v[42:45], v[170:173], v[186:189], v[42:45]
	v_mfma_f32_16x16x32_bf16 v[30:33], v[162:165], v[206:209], v[30:33]
	v_mfma_f32_16x16x32_bf16 v[26:29], v[170:173], v[206:209], v[26:29]
	v_mfma_f32_16x16x32_bf16 v[14:17], v[162:165], v[214:217], v[14:17]
	v_mfma_f32_16x16x32_bf16 v[10:13], v[170:173], v[214:217], v[10:13]
	s_barrier
	s_add_u32 s0, s0, 0x40080
	s_addc_u32 s1, s1, 0
	s_add_i32 s28, s28, s3
	v_lshl_add_u64 v[154:155], s[0:1], 0, v[132:133]
	s_mov_b32 m0, s28
	s_nop 0
	global_load_lds_dwordx4 v[154:155], off
	v_lshl_add_u64 v[154:155], s[0:1], 0, v[136:137]
	s_add_i32 m0, s28, 0x2000
	s_nop 0
	global_load_lds_dwordx4 v[154:155], off
	s_waitcnt vmcnt(6)
	s_barrier
	v_mfma_f32_16x16x32_bf16 v[54:57], v[218:221], v[174:177], v[54:57]
	v_mfma_f32_16x16x32_bf16 v[50:53], v[226:229], v[174:177], v[50:53]
	v_mfma_f32_16x16x32_bf16 v[38:41], v[218:221], v[182:185], v[38:41]
	v_mfma_f32_16x16x32_bf16 v[34:37], v[226:229], v[182:185], v[34:37]
	v_mfma_f32_16x16x32_bf16 v[22:25], v[218:221], v[190:193], v[22:25]
	v_mfma_f32_16x16x32_bf16 v[18:21], v[226:229], v[190:193], v[18:21]
	v_mfma_f32_16x16x32_bf16 v[6:9], v[218:221], v[210:213], v[6:9]
	v_mfma_f32_16x16x32_bf16 v[2:5], v[226:229], v[210:213], v[2:5]
	v_mfma_f32_16x16x32_bf16 v[54:57], v[222:225], v[178:181], v[54:57]
	v_mfma_f32_16x16x32_bf16 v[50:53], v[230:233], v[178:181], v[50:53]
	v_mfma_f32_16x16x32_bf16 v[38:41], v[222:225], v[186:189], v[38:41]
	v_mfma_f32_16x16x32_bf16 v[34:37], v[230:233], v[186:189], v[34:37]
	v_mfma_f32_16x16x32_bf16 v[22:25], v[222:225], v[206:209], v[22:25]
	v_mfma_f32_16x16x32_bf16 v[18:21], v[230:233], v[206:209], v[18:21]
	v_mfma_f32_16x16x32_bf16 v[6:9], v[222:225], v[214:217], v[6:9]
	v_mfma_f32_16x16x32_bf16 v[2:5], v[230:233], v[214:217], v[2:5]
	s_add_i32 s61, s61, 2
	s_add_u32 vcc_lo, vcc_lo, 0x100
	s_addc_u32 vcc_hi, vcc_hi, 0
	s_add_u32 s19, s19, 0x100
	s_addc_u32 s43, s43, 0
	s_cmp_gt_u32 s61, 13
	s_barrier
	s_cbranch_scc0 .LBB0_492

.LBB0_888:
	s_ashr_i32 s5, s4, 31
	s_xor_b64 s[76:77], s[42:43], -1
	s_lshl_b64 s[24:25], s[4:5], 19
	s_add_u32 s40, s86, s24
	s_addc_u32 s41, s87, s25
	s_and_b64 s[24:25], s[42:43], exec
	s_cselect_b32 s5, s41, s63
	s_cselect_b32 s24, s40, s62
	s_ashr_i32 s7, s6, 31
	s_lshl_b64 s[26:27], s[6:7], 19
	s_add_u32 s92, s72, s26
	s_addc_u32 s93, s73, s27
	s_and_b64 s[26:27], s[42:43], exec
	s_cselect_b32 s7, s93, s1
	s_cselect_b32 s25, s92, s0
	s_add_u32 vcc_lo, s62, 0x40080
	s_addc_u32 vcc_hi, s63, 0
	s_add_u32 s26, s0, 0x100
	s_addc_u32 s27, s1, 0
	s_mov_b32 s42, -2
	s_add_u32 s0, vcc_lo, 0xfffc0080
	s_addc_u32 s1, vcc_hi, -1
	s_add_i32 s28, s69, 0x100
	v_add_u32_e32 v0, s28, v151
	ds_read_b128 v[154:157], v0
	ds_read_b128 v[170:173], v0 offset:1024
	ds_read_b128 v[174:177], v0 offset:2048
	ds_read_b128 v[178:181], v0 offset:3072
	s_cmp_eq_u32 s42, 12
	s_cselect_b32 s63, s5, s1
	s_cselect_b32 s62, s24, s0
	s_cselect_b32 s1, s7, s27
	s_cselect_b32 s0, s25, s26
	v_lshl_add_u64 v[158:159], vcc, 0, v[140:141]
	s_add_i32 m0, s9, 0xc000
	ds_read_b128 v[182:185], v168
	ds_read_b128 v[186:189], v168 offset:1024
	ds_read_b128 v[190:193], v168 offset:2048
	ds_read_b128 v[206:209], v168 offset:3072
	ds_read_b128 v[210:213], v168 offset:4096
	ds_read_b128 v[214:217], v168 offset:5120
	ds_read_b128 v[218:221], v168 offset:6144
	ds_read_b128 v[222:225], v168 offset:7168
	global_load_lds_dwordx4 v[158:159], off
	v_lshl_add_u64 v[158:159], vcc, 0, v[142:143]
	s_add_i32 m0, s9, 0xe000
	s_nop 0
	global_load_lds_dwordx4 v[158:159], off
	s_waitcnt lgkmcnt(8)
	s_barrier
	s_waitcnt lgkmcnt(0)
	s_waitcnt lgkmcnt(0)
	v_mfma_f32_16x16x32_bf16 v[126:129], v[154:157], v[182:185], 0
	v_mfma_f32_16x16x32_bf16 v[122:125], v[174:177], v[182:185], 0
	v_mfma_f32_16x16x32_bf16 v[110:113], v[154:157], v[190:193], 0
	v_mfma_f32_16x16x32_bf16 v[106:109], v[174:177], v[190:193], 0
	v_mfma_f32_16x16x32_bf16 v[94:97], v[154:157], v[210:213], 0
	v_mfma_f32_16x16x32_bf16 v[90:93], v[174:177], v[210:213], 0
	v_mfma_f32_16x16x32_bf16 v[78:81], v[154:157], v[218:221], 0
	v_mfma_f32_16x16x32_bf16 v[74:77], v[174:177], v[218:221], 0
	v_mfma_f32_16x16x32_bf16 v[126:129], v[170:173], v[186:189], v[126:129]
	v_mfma_f32_16x16x32_bf16 v[122:125], v[178:181], v[186:189], v[122:125]
	v_mfma_f32_16x16x32_bf16 v[110:113], v[170:173], v[206:209], v[110:113]
	v_mfma_f32_16x16x32_bf16 v[106:109], v[178:181], v[206:209], v[106:109]
	v_mfma_f32_16x16x32_bf16 v[94:97], v[170:173], v[214:217], v[94:97]
	v_mfma_f32_16x16x32_bf16 v[90:93], v[178:181], v[214:217], v[90:93]
	v_mfma_f32_16x16x32_bf16 v[78:81], v[170:173], v[222:225], v[78:81]
	v_mfma_f32_16x16x32_bf16 v[74:77], v[178:181], v[222:225], v[74:77]
	s_barrier
	s_add_i32 s43, s96, 0x100
	s_add_i32 s28, s28, s8
	v_add_u32_e32 v0, s43, v151
	v_lshl_add_u64 v[158:159], s[0:1], 0, v[132:133]
	s_mov_b32 m0, s28
	ds_read_b128 v[226:229], v0
	ds_read_b128 v[230:233], v0 offset:1024
	ds_read_b128 v[234:237], v0 offset:2048
	ds_read_b128 v[238:241], v0 offset:3072
	global_load_lds_dwordx4 v[158:159], off
	v_lshl_add_u64 v[242:243], s[0:1], 0, v[136:137]
	s_add_i32 m0, s28, 0x2000
	s_nop 0
	global_load_lds_dwordx4 v[242:243], off
	s_barrier
	s_waitcnt lgkmcnt(0)
	s_waitcnt lgkmcnt(0)
	v_mfma_f32_16x16x32_bf16 v[118:121], v[226:229], v[182:185], 0
	v_mfma_f32_16x16x32_bf16 v[114:117], v[234:237], v[182:185], 0
	v_mfma_f32_16x16x32_bf16 v[102:105], v[226:229], v[190:193], 0
	v_mfma_f32_16x16x32_bf16 v[98:101], v[234:237], v[190:193], 0
	v_mfma_f32_16x16x32_bf16 v[86:89], v[226:229], v[210:213], 0
	v_mfma_f32_16x16x32_bf16 v[82:85], v[234:237], v[210:213], 0
	v_mfma_f32_16x16x32_bf16 v[70:73], v[226:229], v[218:221], 0
	v_mfma_f32_16x16x32_bf16 v[66:69], v[234:237], v[218:221], 0
	v_mfma_f32_16x16x32_bf16 v[118:121], v[230:233], v[186:189], v[118:121]
	v_mfma_f32_16x16x32_bf16 v[114:117], v[238:241], v[186:189], v[114:117]
	v_mfma_f32_16x16x32_bf16 v[102:105], v[230:233], v[206:209], v[102:105]
	v_mfma_f32_16x16x32_bf16 v[98:101], v[238:241], v[206:209], v[98:101]
	v_mfma_f32_16x16x32_bf16 v[86:89], v[230:233], v[214:217], v[86:89]
	v_mfma_f32_16x16x32_bf16 v[82:85], v[238:241], v[214:217], v[82:85]
	v_mfma_f32_16x16x32_bf16 v[70:73], v[230:233], v[222:225], v[70:73]
	v_mfma_f32_16x16x32_bf16 v[66:69], v[238:241], v[222:225], v[66:69]
	s_mov_b32 m0, s9
	v_lshl_add_u64 v[244:245], s[62:63], 0, v[130:131]
	s_barrier
	ds_read_b128 v[182:185], v168 offset:16384
	ds_read_b128 v[186:189], v168 offset:17408
	ds_read_b128 v[190:193], v168 offset:18432
	ds_read_b128 v[206:209], v168 offset:19456
	ds_read_b128 v[210:213], v168 offset:20480
	ds_read_b128 v[214:217], v168 offset:21504
	ds_read_b128 v[218:221], v168 offset:22528
	ds_read_b128 v[222:225], v168 offset:23552
	global_load_lds_dwordx4 v[244:245], off
	v_lshl_add_u64 v[246:247], s[62:63], 0, v[134:135]
	s_mov_b32 m0, s10
	s_nop 0
	global_load_lds_dwordx4 v[246:247], off
	s_barrier
	s_waitcnt lgkmcnt(0)
	s_waitcnt lgkmcnt(0)
	v_mfma_f32_16x16x32_bf16 v[62:65], v[154:157], v[182:185], 0
	v_mfma_f32_16x16x32_bf16 v[58:61], v[174:177], v[182:185], 0
	v_mfma_f32_16x16x32_bf16 v[46:49], v[154:157], v[190:193], 0
	v_mfma_f32_16x16x32_bf16 v[42:45], v[174:177], v[190:193], 0
	v_mfma_f32_16x16x32_bf16 v[30:33], v[154:157], v[210:213], 0
	v_mfma_f32_16x16x32_bf16 v[26:29], v[174:177], v[210:213], 0
	v_mfma_f32_16x16x32_bf16 v[14:17], v[154:157], v[218:221], 0
	v_mfma_f32_16x16x32_bf16 v[10:13], v[174:177], v[218:221], 0
	v_mfma_f32_16x16x32_bf16 v[62:65], v[170:173], v[186:189], v[62:65]
	v_mfma_f32_16x16x32_bf16 v[58:61], v[178:181], v[186:189], v[58:61]
	v_mfma_f32_16x16x32_bf16 v[46:49], v[170:173], v[206:209], v[46:49]
	v_mfma_f32_16x16x32_bf16 v[42:45], v[178:181], v[206:209], v[42:45]
	v_mfma_f32_16x16x32_bf16 v[30:33], v[170:173], v[214:217], v[30:33]
	v_mfma_f32_16x16x32_bf16 v[26:29], v[178:181], v[214:217], v[26:29]
	v_mfma_f32_16x16x32_bf16 v[14:17], v[170:173], v[222:225], v[14:17]
	v_mfma_f32_16x16x32_bf16 v[10:13], v[178:181], v[222:225], v[10:13]
	s_barrier
	s_add_u32 s28, s0, 0x40000
	s_addc_u32 s29, s1, 0
	s_add_i32 s43, s43, s8
	v_lshl_add_u64 v[154:155], s[28:29], 0, v[132:133]
	s_mov_b32 m0, s43
	s_nop 0
	global_load_lds_dwordx4 v[154:155], off
	v_lshl_add_u64 v[154:155], s[28:29], 0, v[136:137]
	s_add_i32 m0, s43, 0x2000
	s_nop 0
	global_load_lds_dwordx4 v[154:155], off
	s_waitcnt vmcnt(6)
	s_barrier
	v_mfma_f32_16x16x32_bf16 v[54:57], v[226:229], v[182:185], 0
	v_mfma_f32_16x16x32_bf16 v[50:53], v[234:237], v[182:185], 0
	v_mfma_f32_16x16x32_bf16 v[38:41], v[226:229], v[190:193], 0
	v_mfma_f32_16x16x32_bf16 v[34:37], v[234:237], v[190:193], 0
	v_mfma_f32_16x16x32_bf16 v[22:25], v[226:229], v[210:213], 0
	v_mfma_f32_16x16x32_bf16 v[18:21], v[234:237], v[210:213], 0
	v_mfma_f32_16x16x32_bf16 v[6:9], v[226:229], v[218:221], 0
	v_mfma_f32_16x16x32_bf16 v[2:5], v[234:237], v[218:221], 0
	v_mfma_f32_16x16x32_bf16 v[54:57], v[230:233], v[186:189], v[54:57]
	v_mfma_f32_16x16x32_bf16 v[50:53], v[238:241], v[186:189], v[50:53]
	v_mfma_f32_16x16x32_bf16 v[38:41], v[230:233], v[206:209], v[38:41]
	v_mfma_f32_16x16x32_bf16 v[34:37], v[238:241], v[206:209], v[34:37]
	v_mfma_f32_16x16x32_bf16 v[22:25], v[230:233], v[214:217], v[22:25]
	v_mfma_f32_16x16x32_bf16 v[18:21], v[238:241], v[214:217], v[18:21]
	v_mfma_f32_16x16x32_bf16 v[6:9], v[230:233], v[222:225], v[6:9]
	v_mfma_f32_16x16x32_bf16 v[2:5], v[238:241], v[222:225], v[2:5]
	s_add_i32 s43, s97, 0x100
	v_add_u32_e32 v0, s43, v151
	s_barrier
	ds_read_b128 v[154:157], v0
	ds_read_b128 v[170:173], v0 offset:1024
	ds_read_b128 v[174:177], v0 offset:2048
	ds_read_b128 v[178:181], v0 offset:3072
	s_add_u32 s28, s62, 0x40000
	s_addc_u32 s29, s63, 0
	s_mov_b32 m0, s11
	v_lshl_add_u64 v[226:227], s[28:29], 0, v[130:131]
	ds_read_b128 v[182:185], v168 offset:32768
	ds_read_b128 v[186:189], v168 offset:33792
	ds_read_b128 v[190:193], v168 offset:34816
	ds_read_b128 v[206:209], v168 offset:35840
	ds_read_b128 v[210:213], v168 offset:36864
	ds_read_b128 v[214:217], v168 offset:37888
	ds_read_b128 v[218:221], v168 offset:38912
	ds_read_b128 v[222:225], v168 offset:39936
	global_load_lds_dwordx4 v[226:227], off
	v_lshl_add_u64 v[226:227], s[28:29], 0, v[134:135]
	s_mov_b32 m0, s12
	s_nop 0
	global_load_lds_dwordx4 v[226:227], off
	s_waitcnt lgkmcnt(8)
	s_barrier
	s_waitcnt lgkmcnt(0)
	s_waitcnt lgkmcnt(0)
	v_mfma_f32_16x16x32_bf16 v[126:129], v[154:157], v[182:185], v[126:129]
	v_mfma_f32_16x16x32_bf16 v[122:125], v[174:177], v[182:185], v[122:125]
	v_mfma_f32_16x16x32_bf16 v[110:113], v[154:157], v[190:193], v[110:113]
	v_mfma_f32_16x16x32_bf16 v[106:109], v[174:177], v[190:193], v[106:109]
	v_mfma_f32_16x16x32_bf16 v[94:97], v[154:157], v[210:213], v[94:97]
	v_mfma_f32_16x16x32_bf16 v[90:93], v[174:177], v[210:213], v[90:93]
	v_mfma_f32_16x16x32_bf16 v[78:81], v[154:157], v[218:221], v[78:81]
	v_mfma_f32_16x16x32_bf16 v[74:77], v[174:177], v[218:221], v[74:77]
	v_mfma_f32_16x16x32_bf16 v[126:129], v[170:173], v[186:189], v[126:129]
	v_mfma_f32_16x16x32_bf16 v[122:125], v[178:181], v[186:189], v[122:125]
	v_mfma_f32_16x16x32_bf16 v[110:113], v[170:173], v[206:209], v[110:113]
	v_mfma_f32_16x16x32_bf16 v[106:109], v[178:181], v[206:209], v[106:109]
	v_mfma_f32_16x16x32_bf16 v[94:97], v[170:173], v[214:217], v[94:97]
	v_mfma_f32_16x16x32_bf16 v[90:93], v[178:181], v[214:217], v[90:93]
	v_mfma_f32_16x16x32_bf16 v[78:81], v[170:173], v[222:225], v[78:81]
	v_mfma_f32_16x16x32_bf16 v[74:77], v[178:181], v[222:225], v[74:77]
	s_barrier
	s_add_i32 s28, s44, 0x100
	s_add_i32 s29, s43, s8
	v_add_u32_e32 v0, s28, v151
	v_lshl_add_u64 v[158:159], v[158:159], 0, s[46:47]
	s_mov_b32 m0, s29
	ds_read_b128 v[226:229], v0
	ds_read_b128 v[230:233], v0 offset:1024
	ds_read_b128 v[234:237], v0 offset:2048
	ds_read_b128 v[238:241], v0 offset:3072
	global_load_lds_dwordx4 v[158:159], off
	v_lshl_add_u64 v[158:159], v[242:243], 0, s[46:47]
	s_add_i32 m0, s29, 0x2000
	s_nop 0
	global_load_lds_dwordx4 v[158:159], off
	s_barrier
	s_waitcnt lgkmcnt(0)
	s_waitcnt lgkmcnt(0)
	v_mfma_f32_16x16x32_bf16 v[118:121], v[226:229], v[182:185], v[118:121]
	v_mfma_f32_16x16x32_bf16 v[114:117], v[234:237], v[182:185], v[114:117]
	v_mfma_f32_16x16x32_bf16 v[102:105], v[226:229], v[190:193], v[102:105]
	v_mfma_f32_16x16x32_bf16 v[98:101], v[234:237], v[190:193], v[98:101]
	v_mfma_f32_16x16x32_bf16 v[86:89], v[226:229], v[210:213], v[86:89]
	v_mfma_f32_16x16x32_bf16 v[82:85], v[234:237], v[210:213], v[82:85]
	v_mfma_f32_16x16x32_bf16 v[70:73], v[226:229], v[218:221], v[70:73]
	v_mfma_f32_16x16x32_bf16 v[66:69], v[234:237], v[218:221], v[66:69]
	v_mfma_f32_16x16x32_bf16 v[118:121], v[230:233], v[186:189], v[118:121]
	v_mfma_f32_16x16x32_bf16 v[114:117], v[238:241], v[186:189], v[114:117]
	v_mfma_f32_16x16x32_bf16 v[102:105], v[230:233], v[206:209], v[102:105]
	v_mfma_f32_16x16x32_bf16 v[98:101], v[238:241], v[206:209], v[98:101]
	v_mfma_f32_16x16x32_bf16 v[86:89], v[230:233], v[214:217], v[86:89]
	v_mfma_f32_16x16x32_bf16 v[82:85], v[238:241], v[214:217], v[82:85]
	v_mfma_f32_16x16x32_bf16 v[70:73], v[230:233], v[222:225], v[70:73]
	v_mfma_f32_16x16x32_bf16 v[66:69], v[238:241], v[222:225], v[66:69]
	s_mov_b32 m0, s20
	v_lshl_add_u64 v[158:159], v[244:245], 0, s[46:47]
	s_barrier
	ds_read_b128 v[182:185], v168 offset:49152
	ds_read_b128 v[186:189], v168 offset:50176
	ds_read_b128 v[190:193], v168 offset:51200
	ds_read_b128 v[206:209], v168 offset:52224
	ds_read_b128 v[210:213], v168 offset:53248
	ds_read_b128 v[214:217], v168 offset:54272
	ds_read_b128 v[218:221], v168 offset:55296
	ds_read_b128 v[222:225], v168 offset:56320
	global_load_lds_dwordx4 v[158:159], off
	v_lshl_add_u64 v[158:159], v[246:247], 0, s[46:47]
	s_mov_b32 m0, s21
	s_nop 0
	global_load_lds_dwordx4 v[158:159], off
	s_barrier
	s_waitcnt lgkmcnt(0)
	s_waitcnt lgkmcnt(0)
	v_mfma_f32_16x16x32_bf16 v[62:65], v[154:157], v[182:185], v[62:65]
	v_mfma_f32_16x16x32_bf16 v[58:61], v[174:177], v[182:185], v[58:61]
	v_mfma_f32_16x16x32_bf16 v[46:49], v[154:157], v[190:193], v[46:49]
	v_mfma_f32_16x16x32_bf16 v[42:45], v[174:177], v[190:193], v[42:45]
	v_mfma_f32_16x16x32_bf16 v[30:33], v[154:157], v[210:213], v[30:33]
	v_mfma_f32_16x16x32_bf16 v[26:29], v[174:177], v[210:213], v[26:29]
	v_mfma_f32_16x16x32_bf16 v[14:17], v[154:157], v[218:221], v[14:17]
	v_mfma_f32_16x16x32_bf16 v[10:13], v[174:177], v[218:221], v[10:13]
	v_mfma_f32_16x16x32_bf16 v[62:65], v[170:173], v[186:189], v[62:65]
	v_mfma_f32_16x16x32_bf16 v[58:61], v[178:181], v[186:189], v[58:61]
	v_mfma_f32_16x16x32_bf16 v[46:49], v[170:173], v[206:209], v[46:49]
	v_mfma_f32_16x16x32_bf16 v[42:45], v[178:181], v[206:209], v[42:45]
	v_mfma_f32_16x16x32_bf16 v[30:33], v[170:173], v[214:217], v[30:33]
	v_mfma_f32_16x16x32_bf16 v[26:29], v[178:181], v[214:217], v[26:29]
	v_mfma_f32_16x16x32_bf16 v[14:17], v[170:173], v[222:225], v[14:17]
	v_mfma_f32_16x16x32_bf16 v[10:13], v[178:181], v[222:225], v[10:13]
	s_barrier
	s_add_u32 s0, s0, 0x40080
	s_addc_u32 s1, s1, 0
	s_add_i32 s28, s28, s8
	v_lshl_add_u64 v[154:155], s[0:1], 0, v[132:133]
	s_mov_b32 m0, s28
	s_nop 0
	global_load_lds_dwordx4 v[154:155], off
	v_lshl_add_u64 v[154:155], s[0:1], 0, v[136:137]
	s_add_i32 m0, s28, 0x2000
	s_nop 0
	global_load_lds_dwordx4 v[154:155], off
	s_waitcnt vmcnt(6)
	s_barrier
	v_mfma_f32_16x16x32_bf16 v[54:57], v[226:229], v[182:185], v[54:57]
	v_mfma_f32_16x16x32_bf16 v[50:53], v[234:237], v[182:185], v[50:53]
	v_mfma_f32_16x16x32_bf16 v[38:41], v[226:229], v[190:193], v[38:41]
	v_mfma_f32_16x16x32_bf16 v[34:37], v[234:237], v[190:193], v[34:37]
	v_mfma_f32_16x16x32_bf16 v[22:25], v[226:229], v[210:213], v[22:25]
	v_mfma_f32_16x16x32_bf16 v[18:21], v[234:237], v[210:213], v[18:21]
	v_mfma_f32_16x16x32_bf16 v[6:9], v[226:229], v[218:221], v[6:9]
	v_mfma_f32_16x16x32_bf16 v[2:5], v[234:237], v[218:221], v[2:5]
	v_mfma_f32_16x16x32_bf16 v[54:57], v[230:233], v[186:189], v[54:57]
	v_mfma_f32_16x16x32_bf16 v[50:53], v[238:241], v[186:189], v[50:53]
	v_mfma_f32_16x16x32_bf16 v[38:41], v[230:233], v[206:209], v[38:41]
	v_mfma_f32_16x16x32_bf16 v[34:37], v[238:241], v[206:209], v[34:37]
	v_mfma_f32_16x16x32_bf16 v[22:25], v[230:233], v[214:217], v[22:25]
	v_mfma_f32_16x16x32_bf16 v[18:21], v[238:241], v[214:217], v[18:21]
	v_mfma_f32_16x16x32_bf16 v[6:9], v[230:233], v[222:225], v[6:9]
	v_mfma_f32_16x16x32_bf16 v[2:5], v[238:241], v[222:225], v[2:5]
	s_add_i32 s42, s42, 2
	s_add_u32 vcc_lo, vcc_lo, 0x100
	s_addc_u32 vcc_hi, vcc_hi, 0
	s_add_u32 s26, s26, 0x100
	s_addc_u32 s27, s27, 0
	s_cmp_gt_u32 s42, 13
	s_barrier
	s_cbranch_scc1 .Lmy_kexit2
.LBB0_889:
	s_add_u32 s0, vcc_lo, 0xfffc0080
	s_addc_u32 s1, vcc_hi, -1
	s_add_i32 s28, s69, 0x100
	v_add_u32_e32 v0, s28, v151
	ds_read_b128 v[154:157], v0
	ds_read_b128 v[170:173], v0 offset:1024
	ds_read_b128 v[174:177], v0 offset:2048
	ds_read_b128 v[178:181], v0 offset:3072
	s_cmp_eq_u32 s42, 12
	s_cselect_b32 s63, s5, s1
	s_cselect_b32 s62, s24, s0
	s_cselect_b32 s1, s7, s27
	s_cselect_b32 s0, s25, s26
	v_lshl_add_u64 v[158:159], vcc, 0, v[140:141]
	s_add_i32 m0, s9, 0xc000
	ds_read_b128 v[182:185], v168
	ds_read_b128 v[186:189], v168 offset:1024
	ds_read_b128 v[190:193], v168 offset:2048
	ds_read_b128 v[206:209], v168 offset:3072
	ds_read_b128 v[210:213], v168 offset:4096
	ds_read_b128 v[214:217], v168 offset:5120
	ds_read_b128 v[218:221], v168 offset:6144
	ds_read_b128 v[222:225], v168 offset:7168
	global_load_lds_dwordx4 v[158:159], off
	v_lshl_add_u64 v[158:159], vcc, 0, v[142:143]
	s_add_i32 m0, s9, 0xe000
	s_nop 0
	global_load_lds_dwordx4 v[158:159], off
	s_waitcnt lgkmcnt(8)
	s_barrier
	s_waitcnt lgkmcnt(0)
	s_waitcnt lgkmcnt(0)
	v_mfma_f32_16x16x32_bf16 v[126:129], v[154:157], v[182:185], v[126:129]
	v_mfma_f32_16x16x32_bf16 v[122:125], v[174:177], v[182:185], v[122:125]
	v_mfma_f32_16x16x32_bf16 v[110:113], v[154:157], v[190:193], v[110:113]
	v_mfma_f32_16x16x32_bf16 v[106:109], v[174:177], v[190:193], v[106:109]
	v_mfma_f32_16x16x32_bf16 v[94:97], v[154:157], v[210:213], v[94:97]
	v_mfma_f32_16x16x32_bf16 v[90:93], v[174:177], v[210:213], v[90:93]
	v_mfma_f32_16x16x32_bf16 v[78:81], v[154:157], v[218:221], v[78:81]
	v_mfma_f32_16x16x32_bf16 v[74:77], v[174:177], v[218:221], v[74:77]
	v_mfma_f32_16x16x32_bf16 v[126:129], v[170:173], v[186:189], v[126:129]
	v_mfma_f32_16x16x32_bf16 v[122:125], v[178:181], v[186:189], v[122:125]
	v_mfma_f32_16x16x32_bf16 v[110:113], v[170:173], v[206:209], v[110:113]
	v_mfma_f32_16x16x32_bf16 v[106:109], v[178:181], v[206:209], v[106:109]
	v_mfma_f32_16x16x32_bf16 v[94:97], v[170:173], v[214:217], v[94:97]
	v_mfma_f32_16x16x32_bf16 v[90:93], v[178:181], v[214:217], v[90:93]
	v_mfma_f32_16x16x32_bf16 v[78:81], v[170:173], v[222:225], v[78:81]
	v_mfma_f32_16x16x32_bf16 v[74:77], v[178:181], v[222:225], v[74:77]
	s_barrier
	s_add_i32 s43, s96, 0x100
	s_add_i32 s28, s28, s8
	v_add_u32_e32 v0, s43, v151
	v_lshl_add_u64 v[158:159], s[0:1], 0, v[132:133]
	s_mov_b32 m0, s28
	ds_read_b128 v[226:229], v0
	ds_read_b128 v[230:233], v0 offset:1024
	ds_read_b128 v[234:237], v0 offset:2048
	ds_read_b128 v[238:241], v0 offset:3072
	global_load_lds_dwordx4 v[158:159], off
	v_lshl_add_u64 v[242:243], s[0:1], 0, v[136:137]
	s_add_i32 m0, s28, 0x2000
	s_nop 0
	global_load_lds_dwordx4 v[242:243], off
	s_barrier
	s_waitcnt lgkmcnt(0)
	s_waitcnt lgkmcnt(0)
	v_mfma_f32_16x16x32_bf16 v[118:121], v[226:229], v[182:185], v[118:121]
	v_mfma_f32_16x16x32_bf16 v[114:117], v[234:237], v[182:185], v[114:117]
	v_mfma_f32_16x16x32_bf16 v[102:105], v[226:229], v[190:193], v[102:105]
	v_mfma_f32_16x16x32_bf16 v[98:101], v[234:237], v[190:193], v[98:101]
	v_mfma_f32_16x16x32_bf16 v[86:89], v[226:229], v[210:213], v[86:89]
	v_mfma_f32_16x16x32_bf16 v[82:85], v[234:237], v[210:213], v[82:85]
	v_mfma_f32_16x16x32_bf16 v[70:73], v[226:229], v[218:221], v[70:73]
	v_mfma_f32_16x16x32_bf16 v[66:69], v[234:237], v[218:221], v[66:69]
	v_mfma_f32_16x16x32_bf16 v[118:121], v[230:233], v[186:189], v[118:121]
	v_mfma_f32_16x16x32_bf16 v[114:117], v[238:241], v[186:189], v[114:117]
	v_mfma_f32_16x16x32_bf16 v[102:105], v[230:233], v[206:209], v[102:105]
	v_mfma_f32_16x16x32_bf16 v[98:101], v[238:241], v[206:209], v[98:101]
	v_mfma_f32_16x16x32_bf16 v[86:89], v[230:233], v[214:217], v[86:89]
	v_mfma_f32_16x16x32_bf16 v[82:85], v[238:241], v[214:217], v[82:85]
	v_mfma_f32_16x16x32_bf16 v[70:73], v[230:233], v[222:225], v[70:73]
	v_mfma_f32_16x16x32_bf16 v[66:69], v[238:241], v[222:225], v[66:69]
	s_mov_b32 m0, s9
	v_lshl_add_u64 v[244:245], s[62:63], 0, v[130:131]
	s_barrier
	ds_read_b128 v[182:185], v168 offset:16384
	ds_read_b128 v[186:189], v168 offset:17408
	ds_read_b128 v[190:193], v168 offset:18432
	ds_read_b128 v[206:209], v168 offset:19456
	ds_read_b128 v[210:213], v168 offset:20480
	ds_read_b128 v[214:217], v168 offset:21504
	ds_read_b128 v[218:221], v168 offset:22528
	ds_read_b128 v[222:225], v168 offset:23552
	global_load_lds_dwordx4 v[244:245], off
	v_lshl_add_u64 v[246:247], s[62:63], 0, v[134:135]
	s_mov_b32 m0, s10
	s_nop 0
	global_load_lds_dwordx4 v[246:247], off
	s_barrier
	s_waitcnt lgkmcnt(0)
	s_waitcnt lgkmcnt(0)
	v_mfma_f32_16x16x32_bf16 v[62:65], v[154:157], v[182:185], v[62:65]
	v_mfma_f32_16x16x32_bf16 v[58:61], v[174:177], v[182:185], v[58:61]
	v_mfma_f32_16x16x32_bf16 v[46:49], v[154:157], v[190:193], v[46:49]
	v_mfma_f32_16x16x32_bf16 v[42:45], v[174:177], v[190:193], v[42:45]
	v_mfma_f32_16x16x32_bf16 v[30:33], v[154:157], v[210:213], v[30:33]
	v_mfma_f32_16x16x32_bf16 v[26:29], v[174:177], v[210:213], v[26:29]
	v_mfma_f32_16x16x32_bf16 v[14:17], v[154:157], v[218:221], v[14:17]
	v_mfma_f32_16x16x32_bf16 v[10:13], v[174:177], v[218:221], v[10:13]
	v_mfma_f32_16x16x32_bf16 v[62:65], v[170:173], v[186:189], v[62:65]
	v_mfma_f32_16x16x32_bf16 v[58:61], v[178:181], v[186:189], v[58:61]
	v_mfma_f32_16x16x32_bf16 v[46:49], v[170:173], v[206:209], v[46:49]
	v_mfma_f32_16x16x32_bf16 v[42:45], v[178:181], v[206:209], v[42:45]
	v_mfma_f32_16x16x32_bf16 v[30:33], v[170:173], v[214:217], v[30:33]
	v_mfma_f32_16x16x32_bf16 v[26:29], v[178:181], v[214:217], v[26:29]
	v_mfma_f32_16x16x32_bf16 v[14:17], v[170:173], v[222:225], v[14:17]
	v_mfma_f32_16x16x32_bf16 v[10:13], v[178:181], v[222:225], v[10:13]
	s_barrier
	s_add_u32 s28, s0, 0x40000
	s_addc_u32 s29, s1, 0
	s_add_i32 s43, s43, s8
	v_lshl_add_u64 v[154:155], s[28:29], 0, v[132:133]
	s_mov_b32 m0, s43
	s_nop 0
	global_load_lds_dwordx4 v[154:155], off
	v_lshl_add_u64 v[154:155], s[28:29], 0, v[136:137]
	s_add_i32 m0, s43, 0x2000
	s_nop 0
	global_load_lds_dwordx4 v[154:155], off
	s_waitcnt vmcnt(6)
	s_barrier
	v_mfma_f32_16x16x32_bf16 v[54:57], v[226:229], v[182:185], v[54:57]
	v_mfma_f32_16x16x32_bf16 v[50:53], v[234:237], v[182:185], v[50:53]
	v_mfma_f32_16x16x32_bf16 v[38:41], v[226:229], v[190:193], v[38:41]
	v_mfma_f32_16x16x32_bf16 v[34:37], v[234:237], v[190:193], v[34:37]
	v_mfma_f32_16x16x32_bf16 v[22:25], v[226:229], v[210:213], v[22:25]
	v_mfma_f32_16x16x32_bf16 v[18:21], v[234:237], v[210:213], v[18:21]
	v_mfma_f32_16x16x32_bf16 v[6:9], v[226:229], v[218:221], v[6:9]
	v_mfma_f32_16x16x32_bf16 v[2:5], v[234:237], v[218:221], v[2:5]
	v_mfma_f32_16x16x32_bf16 v[54:57], v[230:233], v[186:189], v[54:57]
	v_mfma_f32_16x16x32_bf16 v[50:53], v[238:241], v[186:189], v[50:53]
	v_mfma_f32_16x16x32_bf16 v[38:41], v[230:233], v[206:209], v[38:41]
	v_mfma_f32_16x16x32_bf16 v[34:37], v[238:241], v[206:209], v[34:37]
	v_mfma_f32_16x16x32_bf16 v[22:25], v[230:233], v[214:217], v[22:25]
	v_mfma_f32_16x16x32_bf16 v[18:21], v[238:241], v[214:217], v[18:21]
	v_mfma_f32_16x16x32_bf16 v[6:9], v[230:233], v[222:225], v[6:9]
	v_mfma_f32_16x16x32_bf16 v[2:5], v[238:241], v[222:225], v[2:5]
	s_add_i32 s43, s97, 0x100
	v_add_u32_e32 v0, s43, v151
	s_barrier
	ds_read_b128 v[154:157], v0
	ds_read_b128 v[170:173], v0 offset:1024
	ds_read_b128 v[174:177], v0 offset:2048
	ds_read_b128 v[178:181], v0 offset:3072
	s_add_u32 s28, s62, 0x40000
	s_addc_u32 s29, s63, 0
	s_mov_b32 m0, s11
	v_lshl_add_u64 v[226:227], s[28:29], 0, v[130:131]
	ds_read_b128 v[182:185], v168 offset:32768
	ds_read_b128 v[186:189], v168 offset:33792
	ds_read_b128 v[190:193], v168 offset:34816
	ds_read_b128 v[206:209], v168 offset:35840
	ds_read_b128 v[210:213], v168 offset:36864
	ds_read_b128 v[214:217], v168 offset:37888
	ds_read_b128 v[218:221], v168 offset:38912
	ds_read_b128 v[222:225], v168 offset:39936
	global_load_lds_dwordx4 v[226:227], off
	v_lshl_add_u64 v[226:227], s[28:29], 0, v[134:135]
	s_mov_b32 m0, s12
	s_nop 0
	global_load_lds_dwordx4 v[226:227], off
	s_waitcnt lgkmcnt(8)
	s_barrier
	s_waitcnt lgkmcnt(0)
	s_waitcnt lgkmcnt(0)
	v_mfma_f32_16x16x32_bf16 v[126:129], v[154:157], v[182:185], v[126:129]
	v_mfma_f32_16x16x32_bf16 v[122:125], v[174:177], v[182:185], v[122:125]
	v_mfma_f32_16x16x32_bf16 v[110:113], v[154:157], v[190:193], v[110:113]
	v_mfma_f32_16x16x32_bf16 v[106:109], v[174:177], v[190:193], v[106:109]
	v_mfma_f32_16x16x32_bf16 v[94:97], v[154:157], v[210:213], v[94:97]
	v_mfma_f32_16x16x32_bf16 v[90:93], v[174:177], v[210:213], v[90:93]
	v_mfma_f32_16x16x32_bf16 v[78:81], v[154:157], v[218:221], v[78:81]
	v_mfma_f32_16x16x32_bf16 v[74:77], v[174:177], v[218:221], v[74:77]
	v_mfma_f32_16x16x32_bf16 v[126:129], v[170:173], v[186:189], v[126:129]
	v_mfma_f32_16x16x32_bf16 v[122:125], v[178:181], v[186:189], v[122:125]
	v_mfma_f32_16x16x32_bf16 v[110:113], v[170:173], v[206:209], v[110:113]
	v_mfma_f32_16x16x32_bf16 v[106:109], v[178:181], v[206:209], v[106:109]
	v_mfma_f32_16x16x32_bf16 v[94:97], v[170:173], v[214:217], v[94:97]
	v_mfma_f32_16x16x32_bf16 v[90:93], v[178:181], v[214:217], v[90:93]
	v_mfma_f32_16x16x32_bf16 v[78:81], v[170:173], v[222:225], v[78:81]
	v_mfma_f32_16x16x32_bf16 v[74:77], v[178:181], v[222:225], v[74:77]
	s_barrier
	s_add_i32 s28, s44, 0x100
	s_add_i32 s29, s43, s8
	v_add_u32_e32 v0, s28, v151
	v_lshl_add_u64 v[158:159], v[158:159], 0, s[46:47]
	s_mov_b32 m0, s29
	ds_read_b128 v[226:229], v0
	ds_read_b128 v[230:233], v0 offset:1024
	ds_read_b128 v[234:237], v0 offset:2048
	ds_read_b128 v[238:241], v0 offset:3072
	global_load_lds_dwordx4 v[158:159], off
	v_lshl_add_u64 v[158:159], v[242:243], 0, s[46:47]
	s_add_i32 m0, s29, 0x2000
	s_nop 0
	global_load_lds_dwordx4 v[158:159], off
	s_barrier
	s_waitcnt lgkmcnt(0)
	s_waitcnt lgkmcnt(0)
	v_mfma_f32_16x16x32_bf16 v[118:121], v[226:229], v[182:185], v[118:121]
	v_mfma_f32_16x16x32_bf16 v[114:117], v[234:237], v[182:185], v[114:117]
	v_mfma_f32_16x16x32_bf16 v[102:105], v[226:229], v[190:193], v[102:105]
	v_mfma_f32_16x16x32_bf16 v[98:101], v[234:237], v[190:193], v[98:101]
	v_mfma_f32_16x16x32_bf16 v[86:89], v[226:229], v[210:213], v[86:89]
	v_mfma_f32_16x16x32_bf16 v[82:85], v[234:237], v[210:213], v[82:85]
	v_mfma_f32_16x16x32_bf16 v[70:73], v[226:229], v[218:221], v[70:73]
	v_mfma_f32_16x16x32_bf16 v[66:69], v[234:237], v[218:221], v[66:69]
	v_mfma_f32_16x16x32_bf16 v[118:121], v[230:233], v[186:189], v[118:121]
	v_mfma_f32_16x16x32_bf16 v[114:117], v[238:241], v[186:189], v[114:117]
	v_mfma_f32_16x16x32_bf16 v[102:105], v[230:233], v[206:209], v[102:105]
	v_mfma_f32_16x16x32_bf16 v[98:101], v[238:241], v[206:209], v[98:101]
	v_mfma_f32_16x16x32_bf16 v[86:89], v[230:233], v[214:217], v[86:89]
	v_mfma_f32_16x16x32_bf16 v[82:85], v[238:241], v[214:217], v[82:85]
	v_mfma_f32_16x16x32_bf16 v[70:73], v[230:233], v[222:225], v[70:73]
	v_mfma_f32_16x16x32_bf16 v[66:69], v[238:241], v[222:225], v[66:69]
	s_mov_b32 m0, s20
	v_lshl_add_u64 v[158:159], v[244:245], 0, s[46:47]
	s_barrier
	ds_read_b128 v[182:185], v168 offset:49152
	ds_read_b128 v[186:189], v168 offset:50176
	ds_read_b128 v[190:193], v168 offset:51200
	ds_read_b128 v[206:209], v168 offset:52224
	ds_read_b128 v[210:213], v168 offset:53248
	ds_read_b128 v[214:217], v168 offset:54272
	ds_read_b128 v[218:221], v168 offset:55296
	ds_read_b128 v[222:225], v168 offset:56320
	global_load_lds_dwordx4 v[158:159], off
	v_lshl_add_u64 v[158:159], v[246:247], 0, s[46:47]
	s_mov_b32 m0, s21
	s_nop 0
	global_load_lds_dwordx4 v[158:159], off
	s_barrier
	s_waitcnt lgkmcnt(0)
	s_waitcnt lgkmcnt(0)
	v_mfma_f32_16x16x32_bf16 v[62:65], v[154:157], v[182:185], v[62:65]
	v_mfma_f32_16x16x32_bf16 v[58:61], v[174:177], v[182:185], v[58:61]
	v_mfma_f32_16x16x32_bf16 v[46:49], v[154:157], v[190:193], v[46:49]
	v_mfma_f32_16x16x32_bf16 v[42:45], v[174:177], v[190:193], v[42:45]
	v_mfma_f32_16x16x32_bf16 v[30:33], v[154:157], v[210:213], v[30:33]
	v_mfma_f32_16x16x32_bf16 v[26:29], v[174:177], v[210:213], v[26:29]
	v_mfma_f32_16x16x32_bf16 v[14:17], v[154:157], v[218:221], v[14:17]
	v_mfma_f32_16x16x32_bf16 v[10:13], v[174:177], v[218:221], v[10:13]
	v_mfma_f32_16x16x32_bf16 v[62:65], v[170:173], v[186:189], v[62:65]
	v_mfma_f32_16x16x32_bf16 v[58:61], v[178:181], v[186:189], v[58:61]
	v_mfma_f32_16x16x32_bf16 v[46:49], v[170:173], v[206:209], v[46:49]
	v_mfma_f32_16x16x32_bf16 v[42:45], v[178:181], v[206:209], v[42:45]
	v_mfma_f32_16x16x32_bf16 v[30:33], v[170:173], v[214:217], v[30:33]
	v_mfma_f32_16x16x32_bf16 v[26:29], v[178:181], v[214:217], v[26:29]
	v_mfma_f32_16x16x32_bf16 v[14:17], v[170:173], v[222:225], v[14:17]
	v_mfma_f32_16x16x32_bf16 v[10:13], v[178:181], v[222:225], v[10:13]
	s_barrier
	s_add_u32 s0, s0, 0x40080
	s_addc_u32 s1, s1, 0
	s_add_i32 s28, s28, s8
	v_lshl_add_u64 v[154:155], s[0:1], 0, v[132:133]
	s_mov_b32 m0, s28
	s_nop 0
	global_load_lds_dwordx4 v[154:155], off
	v_lshl_add_u64 v[154:155], s[0:1], 0, v[136:137]
	s_add_i32 m0, s28, 0x2000
	s_nop 0
	global_load_lds_dwordx4 v[154:155], off
	s_waitcnt vmcnt(6)
	s_barrier
	v_mfma_f32_16x16x32_bf16 v[54:57], v[226:229], v[182:185], v[54:57]
	v_mfma_f32_16x16x32_bf16 v[50:53], v[234:237], v[182:185], v[50:53]
	v_mfma_f32_16x16x32_bf16 v[38:41], v[226:229], v[190:193], v[38:41]
	v_mfma_f32_16x16x32_bf16 v[34:37], v[234:237], v[190:193], v[34:37]
	v_mfma_f32_16x16x32_bf16 v[22:25], v[226:229], v[210:213], v[22:25]
	v_mfma_f32_16x16x32_bf16 v[18:21], v[234:237], v[210:213], v[18:21]
	v_mfma_f32_16x16x32_bf16 v[6:9], v[226:229], v[218:221], v[6:9]
	v_mfma_f32_16x16x32_bf16 v[2:5], v[234:237], v[218:221], v[2:5]
	v_mfma_f32_16x16x32_bf16 v[54:57], v[230:233], v[186:189], v[54:57]
	v_mfma_f32_16x16x32_bf16 v[50:53], v[238:241], v[186:189], v[50:53]
	v_mfma_f32_16x16x32_bf16 v[38:41], v[230:233], v[206:209], v[38:41]
	v_mfma_f32_16x16x32_bf16 v[34:37], v[238:241], v[206:209], v[34:37]
	v_mfma_f32_16x16x32_bf16 v[22:25], v[230:233], v[214:217], v[22:25]
	v_mfma_f32_16x16x32_bf16 v[18:21], v[238:241], v[214:217], v[18:21]
	v_mfma_f32_16x16x32_bf16 v[6:9], v[230:233], v[222:225], v[6:9]
	v_mfma_f32_16x16x32_bf16 v[2:5], v[238:241], v[222:225], v[2:5]
	s_add_i32 s42, s42, 2
	s_add_u32 vcc_lo, vcc_lo, 0x100
	s_addc_u32 vcc_hi, vcc_hi, 0
	s_add_u32 s26, s26, 0x100
	s_addc_u32 s27, s27, 0
	s_cmp_gt_u32 s42, 13
	s_barrier
	s_cbranch_scc0 .LBB0_889
